# state kept in row-pair layout across chunks: no v_swap in the loop (10 of 12 removed, 8 idle cycles kept in front of step loop 1), Lambda scaling with op_sel, two swaps on the exit path, corrected lgk
# baseline (speedup 1.0000x reference)
.LBB0_409:
	s_waitcnt lgkmcnt(0)
	v_pk_mul_f32 v[16:17], v[92:93], v[12:13] op_sel_hi:[1,0]
	v_pk_mul_f32 v[18:19], v[32:33], v[14:15] op_sel_hi:[1,0]
	v_pk_mul_f32 v[12:13], v[94:95], v[12:13] op_sel:[0,1]
	v_pk_mul_f32 v[14:15], v[34:35], v[14:15] op_sel:[0,1]
	s_xor_b64 s[62:63], s[62:63], -1
	s_xor_b64 s[64:65], s[64:65], -1
	s_and_b64 vcc, exec, s[66:67]
	s_barrier
	s_cbranch_vccnz .LBB0_444

.LBB0_415:
	s_nop 3
	s_nop 3
	s_waitcnt lgkmcnt(0)
	v_pk_mul_f32 v[132:133], v[16:17], v[32:33] op_sel_hi:[1,0]
	v_pk_fma_f32 v[132:133], v[12:13], v[32:33], v[132:133] op_sel:[0,1,0]
	v_pk_fma_f32 v[132:133], v[18:19], v[34:35], v[132:133] op_sel_hi:[1,0,1]
	v_pk_fma_f32 v[132:133], v[14:15], v[34:35], v[132:133] op_sel:[0,1,0]
	ds_read_b128 v[94:97], v42 offset:12288
	ds_read_b128 v[116:119], v42 offset:16384
	ds_read_b128 v[120:123], v42 offset:8192
	ds_read_b128 v[124:127], v42
	ds_read_b64 v[130:131], v92
	v_pk_fma_f32 v[16:17], v[28:29], v[90:91], v[16:17] op_sel_hi:[0,1,1]
	v_pk_fma_f32 v[12:13], v[28:29], v[90:91], v[12:13] op_sel:[1,0,0]
	v_add_f32_dpp v132, v132, v132 quad_perm:[1,0,3,2] row_mask:0xf bank_mask:0xf bound_ctrl:1
	v_add_f32_dpp v133, v133, v133 quad_perm:[1,0,3,2] row_mask:0xf bank_mask:0xf bound_ctrl:1
	v_pk_fma_f32 v[18:19], v[30:31], v[90:91], v[18:19] op_sel_hi:[0,1,1]
	v_add_f32_dpp v132, v132, v132 quad_perm:[2,3,0,1] row_mask:0xf bank_mask:0xf bound_ctrl:1
	v_add_f32_dpp v133, v133, v133 quad_perm:[2,3,0,1] row_mask:0xf bank_mask:0xf bound_ctrl:1
	v_pk_fma_f32 v[14:15], v[30:31], v[90:91], v[14:15] op_sel:[1,0,0]
	v_add_f32_dpp v132, v132, v132 row_half_mirror row_mask:0xf bank_mask:0xf bound_ctrl:1
	v_add_f32_dpp v133, v133, v133 row_half_mirror row_mask:0xf bank_mask:0xf bound_ctrl:1
	ds_read_b64 v[90:91], v115 offset:20736
	v_add_f32_dpp v132, v132, v132 row_mirror row_mask:0xf bank_mask:0xf bound_ctrl:1
	v_add_f32_dpp v133, v133, v133 row_mirror row_mask:0xf bank_mask:0xf bound_ctrl:1
	v_pk_fma_f32 v[16:17], v[24:25], v[132:133], v[16:17] op_sel_hi:[0,1,1]
	v_pk_fma_f32 v[12:13], v[24:25], v[132:133], v[12:13] op_sel:[1,0,0]
	v_pk_fma_f32 v[18:19], v[26:27], v[132:133], v[18:19] op_sel_hi:[0,1,1]
	v_pk_fma_f32 v[14:15], v[26:27], v[132:133], v[14:15] op_sel:[1,0,0]
	s_waitcnt lgkmcnt(1)
	v_pk_mul_f32 v[132:133], v[16:17], v[94:95] op_sel_hi:[1,0]
	v_pk_mul_f32 v[24:25], v[16:17], v[20:21] op_sel_hi:[1,0]
	v_pk_fma_f32 v[132:133], v[12:13], v[94:95], v[132:133] op_sel:[0,1,0]
	v_pk_fma_f32 v[24:25], v[12:13], v[20:21], v[24:25] op_sel:[0,1,0]
	v_pk_fma_f32 v[132:133], v[18:19], v[96:97], v[132:133] op_sel_hi:[1,0,1]
	v_pk_fma_f32 v[24:25], v[18:19], v[22:23], v[24:25] op_sel_hi:[1,0,1]
	v_pk_fma_f32 v[132:133], v[14:15], v[96:97], v[132:133] op_sel:[0,1,0]
	v_pk_fma_f32 v[24:25], v[14:15], v[22:23], v[24:25] op_sel:[0,1,0]
	v_cvt_pk_f16_f32 v96, v24, v25
	v_add_f32_dpp v132, v132, v132 quad_perm:[1,0,3,2] row_mask:0xf bank_mask:0xf bound_ctrl:1
	v_add_f32_dpp v133, v133, v133 quad_perm:[1,0,3,2] row_mask:0xf bank_mask:0xf bound_ctrl:1
	ds_read_b128 v[32:35], v114 offset:12800
	ds_read_b128 v[24:27], v114 offset:16896
	ds_read_b128 v[28:31], v114 offset:8704
	ds_read_b128 v[20:23], v114 offset:512
	v_pk_fma_f32 v[16:17], v[120:121], v[130:131], v[16:17] op_sel_hi:[0,1,1]
	v_add_f32_dpp v132, v132, v132 quad_perm:[2,3,0,1] row_mask:0xf bank_mask:0xf bound_ctrl:1
	v_add_f32_dpp v133, v133, v133 quad_perm:[2,3,0,1] row_mask:0xf bank_mask:0xf bound_ctrl:1
	v_pk_fma_f32 v[12:13], v[120:121], v[130:131], v[12:13] op_sel:[1,0,0]
	v_add_f32_dpp v132, v132, v132 row_half_mirror row_mask:0xf bank_mask:0xf bound_ctrl:1
	v_add_f32_dpp v133, v133, v133 row_half_mirror row_mask:0xf bank_mask:0xf bound_ctrl:1
	v_pk_fma_f32 v[18:19], v[122:123], v[130:131], v[18:19] op_sel_hi:[0,1,1]
	v_pk_fma_f32 v[14:15], v[122:123], v[130:131], v[14:15] op_sel:[1,0,0]
	v_add_f32_dpp v132, v132, v132 row_mirror row_mask:0xf bank_mask:0xf bound_ctrl:1
	v_add_f32_dpp v133, v133, v133 row_mirror row_mask:0xf bank_mask:0xf bound_ctrl:1
	v_pk_fma_f32 v[16:17], v[116:117], v[132:133], v[16:17] op_sel_hi:[0,1,1]
	v_pk_fma_f32 v[12:13], v[116:117], v[132:133], v[12:13] op_sel:[1,0,0]
	v_pk_fma_f32 v[18:19], v[118:119], v[132:133], v[18:19] op_sel_hi:[0,1,1]
	v_pk_fma_f32 v[14:15], v[118:119], v[132:133], v[14:15] op_sel:[1,0,0]
	s_waitcnt lgkmcnt(0)
	v_pk_mul_f32 v[132:133], v[16:17], v[32:33] op_sel_hi:[1,0]
	v_pk_mul_f32 v[94:95], v[16:17], v[124:125] op_sel_hi:[1,0]
	v_pk_fma_f32 v[132:133], v[12:13], v[32:33], v[132:133] op_sel:[0,1,0]
	v_pk_fma_f32 v[94:95], v[12:13], v[124:125], v[94:95] op_sel:[0,1,0]
	v_pk_fma_f32 v[132:133], v[18:19], v[34:35], v[132:133] op_sel_hi:[1,0,1]
	v_pk_fma_f32 v[94:95], v[18:19], v[126:127], v[94:95] op_sel_hi:[1,0,1]
	v_pk_fma_f32 v[132:133], v[14:15], v[34:35], v[132:133] op_sel:[0,1,0]
	v_pk_fma_f32 v[94:95], v[14:15], v[126:127], v[94:95] op_sel:[0,1,0]
	v_cvt_pk_f16_f32 v94, v94, v95
	v_add_f32_dpp v132, v132, v132 quad_perm:[1,0,3,2] row_mask:0xf bank_mask:0xf bound_ctrl:1
	v_add_f32_dpp v133, v133, v133 quad_perm:[1,0,3,2] row_mask:0xf bank_mask:0xf bound_ctrl:1
	ds_write2st64_b32 v93, v96, v94 offset0:0 offset1:4
	ds_read_b128 v[94:97], v42 offset:12800
	ds_read_b128 v[116:119], v42 offset:16896
	ds_read_b128 v[120:123], v42 offset:8704
	ds_read_b128 v[124:127], v42 offset:512
	ds_read_b64 v[130:131], v92 offset:256
	v_pk_fma_f32 v[16:17], v[28:29], v[90:91], v[16:17] op_sel_hi:[0,1,1]
	v_add_f32_dpp v132, v132, v132 quad_perm:[2,3,0,1] row_mask:0xf bank_mask:0xf bound_ctrl:1
	v_add_f32_dpp v133, v133, v133 quad_perm:[2,3,0,1] row_mask:0xf bank_mask:0xf bound_ctrl:1
	v_pk_fma_f32 v[12:13], v[28:29], v[90:91], v[12:13] op_sel:[1,0,0]
	v_add_f32_dpp v132, v132, v132 row_half_mirror row_mask:0xf bank_mask:0xf bound_ctrl:1
	v_add_f32_dpp v133, v133, v133 row_half_mirror row_mask:0xf bank_mask:0xf bound_ctrl:1
	v_pk_fma_f32 v[18:19], v[30:31], v[90:91], v[18:19] op_sel_hi:[0,1,1]
	v_pk_fma_f32 v[14:15], v[30:31], v[90:91], v[14:15] op_sel:[1,0,0]
	ds_read_b64 v[90:91], v115 offset:20992
	v_add_f32_dpp v132, v132, v132 row_mirror row_mask:0xf bank_mask:0xf bound_ctrl:1
	v_add_f32_dpp v133, v133, v133 row_mirror row_mask:0xf bank_mask:0xf bound_ctrl:1
	v_pk_fma_f32 v[16:17], v[24:25], v[132:133], v[16:17] op_sel_hi:[0,1,1]
	v_pk_fma_f32 v[12:13], v[24:25], v[132:133], v[12:13] op_sel:[1,0,0]
	v_pk_fma_f32 v[18:19], v[26:27], v[132:133], v[18:19] op_sel_hi:[0,1,1]
	v_pk_fma_f32 v[14:15], v[26:27], v[132:133], v[14:15] op_sel:[1,0,0]
	s_waitcnt lgkmcnt(1)
	v_pk_mul_f32 v[132:133], v[16:17], v[94:95] op_sel_hi:[1,0]
	v_pk_mul_f32 v[24:25], v[16:17], v[20:21] op_sel_hi:[1,0]
	v_pk_fma_f32 v[132:133], v[12:13], v[94:95], v[132:133] op_sel:[0,1,0]
	v_pk_fma_f32 v[24:25], v[12:13], v[20:21], v[24:25] op_sel:[0,1,0]
	v_pk_fma_f32 v[132:133], v[18:19], v[96:97], v[132:133] op_sel_hi:[1,0,1]
	v_pk_fma_f32 v[24:25], v[18:19], v[22:23], v[24:25] op_sel_hi:[1,0,1]
	v_pk_fma_f32 v[132:133], v[14:15], v[96:97], v[132:133] op_sel:[0,1,0]
	v_pk_fma_f32 v[24:25], v[14:15], v[22:23], v[24:25] op_sel:[0,1,0]
	v_cvt_pk_f16_f32 v96, v24, v25
	v_add_f32_dpp v132, v132, v132 quad_perm:[1,0,3,2] row_mask:0xf bank_mask:0xf bound_ctrl:1
	v_add_f32_dpp v133, v133, v133 quad_perm:[1,0,3,2] row_mask:0xf bank_mask:0xf bound_ctrl:1
	ds_read_b128 v[32:35], v114 offset:13312
	ds_read_b128 v[24:27], v114 offset:17408
	ds_read_b128 v[28:31], v114 offset:9216
	ds_read_b128 v[20:23], v114 offset:1024
	v_pk_fma_f32 v[16:17], v[120:121], v[130:131], v[16:17] op_sel_hi:[0,1,1]
	v_add_f32_dpp v132, v132, v132 quad_perm:[2,3,0,1] row_mask:0xf bank_mask:0xf bound_ctrl:1
	v_add_f32_dpp v133, v133, v133 quad_perm:[2,3,0,1] row_mask:0xf bank_mask:0xf bound_ctrl:1
	v_pk_fma_f32 v[12:13], v[120:121], v[130:131], v[12:13] op_sel:[1,0,0]
	v_add_f32_dpp v132, v132, v132 row_half_mirror row_mask:0xf bank_mask:0xf bound_ctrl:1
	v_add_f32_dpp v133, v133, v133 row_half_mirror row_mask:0xf bank_mask:0xf bound_ctrl:1
	v_pk_fma_f32 v[18:19], v[122:123], v[130:131], v[18:19] op_sel_hi:[0,1,1]
	v_pk_fma_f32 v[14:15], v[122:123], v[130:131], v[14:15] op_sel:[1,0,0]
	v_add_f32_dpp v132, v132, v132 row_mirror row_mask:0xf bank_mask:0xf bound_ctrl:1
	v_add_f32_dpp v133, v133, v133 row_mirror row_mask:0xf bank_mask:0xf bound_ctrl:1
	v_pk_fma_f32 v[16:17], v[116:117], v[132:133], v[16:17] op_sel_hi:[0,1,1]
	v_pk_fma_f32 v[12:13], v[116:117], v[132:133], v[12:13] op_sel:[1,0,0]
	v_pk_fma_f32 v[18:19], v[118:119], v[132:133], v[18:19] op_sel_hi:[0,1,1]
	v_pk_fma_f32 v[14:15], v[118:119], v[132:133], v[14:15] op_sel:[1,0,0]
	s_waitcnt lgkmcnt(0)
	v_pk_mul_f32 v[132:133], v[16:17], v[32:33] op_sel_hi:[1,0]
	v_pk_mul_f32 v[94:95], v[16:17], v[124:125] op_sel_hi:[1,0]
	v_pk_fma_f32 v[132:133], v[12:13], v[32:33], v[132:133] op_sel:[0,1,0]
	v_pk_fma_f32 v[94:95], v[12:13], v[124:125], v[94:95] op_sel:[0,1,0]
	v_pk_fma_f32 v[132:133], v[18:19], v[34:35], v[132:133] op_sel_hi:[1,0,1]
	v_pk_fma_f32 v[94:95], v[18:19], v[126:127], v[94:95] op_sel_hi:[1,0,1]
	v_pk_fma_f32 v[132:133], v[14:15], v[34:35], v[132:133] op_sel:[0,1,0]
	v_pk_fma_f32 v[94:95], v[14:15], v[126:127], v[94:95] op_sel:[0,1,0]
	v_cvt_pk_f16_f32 v94, v94, v95
	v_add_f32_dpp v132, v132, v132 quad_perm:[1,0,3,2] row_mask:0xf bank_mask:0xf bound_ctrl:1
	v_add_f32_dpp v133, v133, v133 quad_perm:[1,0,3,2] row_mask:0xf bank_mask:0xf bound_ctrl:1
	ds_write2st64_b32 v93, v96, v94 offset0:8 offset1:12
	ds_read_b128 v[94:97], v42 offset:13312
	ds_read_b128 v[116:119], v42 offset:17408
	ds_read_b128 v[120:123], v42 offset:9216
	ds_read_b128 v[124:127], v42 offset:1024
	ds_read_b64 v[130:131], v92 offset:512
	v_pk_fma_f32 v[16:17], v[28:29], v[90:91], v[16:17] op_sel_hi:[0,1,1]
	v_add_f32_dpp v132, v132, v132 quad_perm:[2,3,0,1] row_mask:0xf bank_mask:0xf bound_ctrl:1
	v_add_f32_dpp v133, v133, v133 quad_perm:[2,3,0,1] row_mask:0xf bank_mask:0xf bound_ctrl:1
	v_pk_fma_f32 v[12:13], v[28:29], v[90:91], v[12:13] op_sel:[1,0,0]
	v_add_f32_dpp v132, v132, v132 row_half_mirror row_mask:0xf bank_mask:0xf bound_ctrl:1
	v_add_f32_dpp v133, v133, v133 row_half_mirror row_mask:0xf bank_mask:0xf bound_ctrl:1
	v_pk_fma_f32 v[18:19], v[30:31], v[90:91], v[18:19] op_sel_hi:[0,1,1]
	v_pk_fma_f32 v[14:15], v[30:31], v[90:91], v[14:15] op_sel:[1,0,0]
	ds_read_b64 v[90:91], v115 offset:21248
	v_add_f32_dpp v132, v132, v132 row_mirror row_mask:0xf bank_mask:0xf bound_ctrl:1
	v_add_f32_dpp v133, v133, v133 row_mirror row_mask:0xf bank_mask:0xf bound_ctrl:1
	v_pk_fma_f32 v[16:17], v[24:25], v[132:133], v[16:17] op_sel_hi:[0,1,1]
	v_pk_fma_f32 v[12:13], v[24:25], v[132:133], v[12:13] op_sel:[1,0,0]
	v_pk_fma_f32 v[18:19], v[26:27], v[132:133], v[18:19] op_sel_hi:[0,1,1]
	v_pk_fma_f32 v[14:15], v[26:27], v[132:133], v[14:15] op_sel:[1,0,0]
	s_waitcnt lgkmcnt(1)
	v_pk_mul_f32 v[132:133], v[16:17], v[94:95] op_sel_hi:[1,0]
	v_pk_mul_f32 v[24:25], v[16:17], v[20:21] op_sel_hi:[1,0]
	v_pk_fma_f32 v[132:133], v[12:13], v[94:95], v[132:133] op_sel:[0,1,0]
	v_pk_fma_f32 v[24:25], v[12:13], v[20:21], v[24:25] op_sel:[0,1,0]
	v_pk_fma_f32 v[132:133], v[18:19], v[96:97], v[132:133] op_sel_hi:[1,0,1]
	v_pk_fma_f32 v[24:25], v[18:19], v[22:23], v[24:25] op_sel_hi:[1,0,1]
	v_pk_fma_f32 v[132:133], v[14:15], v[96:97], v[132:133] op_sel:[0,1,0]
	v_pk_fma_f32 v[24:25], v[14:15], v[22:23], v[24:25] op_sel:[0,1,0]
	v_cvt_pk_f16_f32 v96, v24, v25
	v_add_f32_dpp v132, v132, v132 quad_perm:[1,0,3,2] row_mask:0xf bank_mask:0xf bound_ctrl:1
	v_add_f32_dpp v133, v133, v133 quad_perm:[1,0,3,2] row_mask:0xf bank_mask:0xf bound_ctrl:1
	ds_read_b128 v[32:35], v114 offset:13824
	ds_read_b128 v[24:27], v114 offset:17920
	ds_read_b128 v[28:31], v114 offset:9728
	ds_read_b128 v[20:23], v114 offset:1536
	v_pk_fma_f32 v[16:17], v[120:121], v[130:131], v[16:17] op_sel_hi:[0,1,1]
	v_add_f32_dpp v132, v132, v132 quad_perm:[2,3,0,1] row_mask:0xf bank_mask:0xf bound_ctrl:1
	v_add_f32_dpp v133, v133, v133 quad_perm:[2,3,0,1] row_mask:0xf bank_mask:0xf bound_ctrl:1
	v_pk_fma_f32 v[12:13], v[120:121], v[130:131], v[12:13] op_sel:[1,0,0]
	v_add_f32_dpp v132, v132, v132 row_half_mirror row_mask:0xf bank_mask:0xf bound_ctrl:1
	v_add_f32_dpp v133, v133, v133 row_half_mirror row_mask:0xf bank_mask:0xf bound_ctrl:1
	v_pk_fma_f32 v[18:19], v[122:123], v[130:131], v[18:19] op_sel_hi:[0,1,1]
	v_pk_fma_f32 v[14:15], v[122:123], v[130:131], v[14:15] op_sel:[1,0,0]
	v_add_f32_dpp v132, v132, v132 row_mirror row_mask:0xf bank_mask:0xf bound_ctrl:1
	v_add_f32_dpp v133, v133, v133 row_mirror row_mask:0xf bank_mask:0xf bound_ctrl:1
	v_pk_fma_f32 v[16:17], v[116:117], v[132:133], v[16:17] op_sel_hi:[0,1,1]
	v_pk_fma_f32 v[12:13], v[116:117], v[132:133], v[12:13] op_sel:[1,0,0]
	v_pk_fma_f32 v[18:19], v[118:119], v[132:133], v[18:19] op_sel_hi:[0,1,1]
	v_pk_fma_f32 v[14:15], v[118:119], v[132:133], v[14:15] op_sel:[1,0,0]
	s_waitcnt lgkmcnt(0)
	v_pk_mul_f32 v[132:133], v[16:17], v[32:33] op_sel_hi:[1,0]
	v_pk_mul_f32 v[94:95], v[16:17], v[124:125] op_sel_hi:[1,0]
	v_pk_fma_f32 v[132:133], v[12:13], v[32:33], v[132:133] op_sel:[0,1,0]
	v_pk_fma_f32 v[94:95], v[12:13], v[124:125], v[94:95] op_sel:[0,1,0]
	v_pk_fma_f32 v[132:133], v[18:19], v[34:35], v[132:133] op_sel_hi:[1,0,1]
	v_pk_fma_f32 v[94:95], v[18:19], v[126:127], v[94:95] op_sel_hi:[1,0,1]
	v_pk_fma_f32 v[132:133], v[14:15], v[34:35], v[132:133] op_sel:[0,1,0]
	v_pk_fma_f32 v[94:95], v[14:15], v[126:127], v[94:95] op_sel:[0,1,0]
	v_cvt_pk_f16_f32 v94, v94, v95
	v_add_f32_dpp v132, v132, v132 quad_perm:[1,0,3,2] row_mask:0xf bank_mask:0xf bound_ctrl:1
	v_add_f32_dpp v133, v133, v133 quad_perm:[1,0,3,2] row_mask:0xf bank_mask:0xf bound_ctrl:1
	ds_write2st64_b32 v93, v96, v94 offset0:16 offset1:20
	ds_read_b128 v[94:97], v42 offset:13824
	ds_read_b128 v[116:119], v42 offset:17920
	ds_read_b128 v[120:123], v42 offset:9728
	ds_read_b128 v[124:127], v42 offset:1536
	ds_read_b64 v[130:131], v92 offset:768
	v_pk_fma_f32 v[16:17], v[28:29], v[90:91], v[16:17] op_sel_hi:[0,1,1]
	v_add_f32_dpp v132, v132, v132 quad_perm:[2,3,0,1] row_mask:0xf bank_mask:0xf bound_ctrl:1
	v_add_f32_dpp v133, v133, v133 quad_perm:[2,3,0,1] row_mask:0xf bank_mask:0xf bound_ctrl:1
	v_pk_fma_f32 v[12:13], v[28:29], v[90:91], v[12:13] op_sel:[1,0,0]
	v_add_f32_dpp v132, v132, v132 row_half_mirror row_mask:0xf bank_mask:0xf bound_ctrl:1
	v_add_f32_dpp v133, v133, v133 row_half_mirror row_mask:0xf bank_mask:0xf bound_ctrl:1
	v_pk_fma_f32 v[18:19], v[30:31], v[90:91], v[18:19] op_sel_hi:[0,1,1]
	v_pk_fma_f32 v[14:15], v[30:31], v[90:91], v[14:15] op_sel:[1,0,0]
	ds_read_b64 v[90:91], v115 offset:21504
	v_add_f32_dpp v132, v132, v132 row_mirror row_mask:0xf bank_mask:0xf bound_ctrl:1
	v_add_f32_dpp v133, v133, v133 row_mirror row_mask:0xf bank_mask:0xf bound_ctrl:1
	v_pk_fma_f32 v[16:17], v[24:25], v[132:133], v[16:17] op_sel_hi:[0,1,1]
	v_pk_fma_f32 v[12:13], v[24:25], v[132:133], v[12:13] op_sel:[1,0,0]
	v_pk_fma_f32 v[18:19], v[26:27], v[132:133], v[18:19] op_sel_hi:[0,1,1]
	v_pk_fma_f32 v[14:15], v[26:27], v[132:133], v[14:15] op_sel:[1,0,0]
	s_waitcnt lgkmcnt(1)
	v_pk_mul_f32 v[132:133], v[16:17], v[94:95] op_sel_hi:[1,0]
	v_pk_mul_f32 v[24:25], v[16:17], v[20:21] op_sel_hi:[1,0]
	v_pk_fma_f32 v[132:133], v[12:13], v[94:95], v[132:133] op_sel:[0,1,0]
	v_pk_fma_f32 v[24:25], v[12:13], v[20:21], v[24:25] op_sel:[0,1,0]
	v_pk_fma_f32 v[132:133], v[18:19], v[96:97], v[132:133] op_sel_hi:[1,0,1]
	v_pk_fma_f32 v[24:25], v[18:19], v[22:23], v[24:25] op_sel_hi:[1,0,1]
	v_pk_fma_f32 v[132:133], v[14:15], v[96:97], v[132:133] op_sel:[0,1,0]
	v_pk_fma_f32 v[24:25], v[14:15], v[22:23], v[24:25] op_sel:[0,1,0]
	v_cvt_pk_f16_f32 v96, v24, v25
	v_add_f32_dpp v132, v132, v132 quad_perm:[1,0,3,2] row_mask:0xf bank_mask:0xf bound_ctrl:1
	v_add_f32_dpp v133, v133, v133 quad_perm:[1,0,3,2] row_mask:0xf bank_mask:0xf bound_ctrl:1
	ds_read_b128 v[32:35], v114 offset:14336
	ds_read_b128 v[24:27], v114 offset:18432
	ds_read_b128 v[28:31], v114 offset:10240
	ds_read_b128 v[20:23], v114 offset:2048
	v_pk_fma_f32 v[16:17], v[120:121], v[130:131], v[16:17] op_sel_hi:[0,1,1]
	v_add_f32_dpp v132, v132, v132 quad_perm:[2,3,0,1] row_mask:0xf bank_mask:0xf bound_ctrl:1
	v_add_f32_dpp v133, v133, v133 quad_perm:[2,3,0,1] row_mask:0xf bank_mask:0xf bound_ctrl:1
	v_pk_fma_f32 v[12:13], v[120:121], v[130:131], v[12:13] op_sel:[1,0,0]
	v_add_f32_dpp v132, v132, v132 row_half_mirror row_mask:0xf bank_mask:0xf bound_ctrl:1
	v_add_f32_dpp v133, v133, v133 row_half_mirror row_mask:0xf bank_mask:0xf bound_ctrl:1
	v_pk_fma_f32 v[18:19], v[122:123], v[130:131], v[18:19] op_sel_hi:[0,1,1]
	v_pk_fma_f32 v[14:15], v[122:123], v[130:131], v[14:15] op_sel:[1,0,0]
	v_add_f32_dpp v132, v132, v132 row_mirror row_mask:0xf bank_mask:0xf bound_ctrl:1
	v_add_f32_dpp v133, v133, v133 row_mirror row_mask:0xf bank_mask:0xf bound_ctrl:1
	v_pk_fma_f32 v[16:17], v[116:117], v[132:133], v[16:17] op_sel_hi:[0,1,1]
	v_pk_fma_f32 v[12:13], v[116:117], v[132:133], v[12:13] op_sel:[1,0,0]
	v_pk_fma_f32 v[18:19], v[118:119], v[132:133], v[18:19] op_sel_hi:[0,1,1]
	v_pk_fma_f32 v[14:15], v[118:119], v[132:133], v[14:15] op_sel:[1,0,0]
	s_waitcnt lgkmcnt(0)
	v_pk_mul_f32 v[132:133], v[16:17], v[32:33] op_sel_hi:[1,0]
	v_pk_mul_f32 v[94:95], v[16:17], v[124:125] op_sel_hi:[1,0]
	v_pk_fma_f32 v[132:133], v[12:13], v[32:33], v[132:133] op_sel:[0,1,0]
	v_pk_fma_f32 v[94:95], v[12:13], v[124:125], v[94:95] op_sel:[0,1,0]
	v_pk_fma_f32 v[132:133], v[18:19], v[34:35], v[132:133] op_sel_hi:[1,0,1]
	v_pk_fma_f32 v[94:95], v[18:19], v[126:127], v[94:95] op_sel_hi:[1,0,1]
	v_pk_fma_f32 v[132:133], v[14:15], v[34:35], v[132:133] op_sel:[0,1,0]
	v_pk_fma_f32 v[94:95], v[14:15], v[126:127], v[94:95] op_sel:[0,1,0]
	v_cvt_pk_f16_f32 v94, v94, v95
	v_add_f32_dpp v132, v132, v132 quad_perm:[1,0,3,2] row_mask:0xf bank_mask:0xf bound_ctrl:1
	v_add_f32_dpp v133, v133, v133 quad_perm:[1,0,3,2] row_mask:0xf bank_mask:0xf bound_ctrl:1
	ds_write2st64_b32 v93, v96, v94 offset0:24 offset1:28
	ds_read_b128 v[94:97], v42 offset:14336
	ds_read_b128 v[116:119], v42 offset:18432
	ds_read_b128 v[120:123], v42 offset:10240
	ds_read_b128 v[124:127], v42 offset:2048
	ds_read_b64 v[130:131], v92 offset:1024
	v_pk_fma_f32 v[16:17], v[28:29], v[90:91], v[16:17] op_sel_hi:[0,1,1]
	v_add_f32_dpp v132, v132, v132 quad_perm:[2,3,0,1] row_mask:0xf bank_mask:0xf bound_ctrl:1
	v_add_f32_dpp v133, v133, v133 quad_perm:[2,3,0,1] row_mask:0xf bank_mask:0xf bound_ctrl:1
	v_pk_fma_f32 v[12:13], v[28:29], v[90:91], v[12:13] op_sel:[1,0,0]
	v_add_f32_dpp v132, v132, v132 row_half_mirror row_mask:0xf bank_mask:0xf bound_ctrl:1
	v_add_f32_dpp v133, v133, v133 row_half_mirror row_mask:0xf bank_mask:0xf bound_ctrl:1
	v_pk_fma_f32 v[18:19], v[30:31], v[90:91], v[18:19] op_sel_hi:[0,1,1]
	v_pk_fma_f32 v[14:15], v[30:31], v[90:91], v[14:15] op_sel:[1,0,0]
	ds_read_b64 v[90:91], v115 offset:21760
	v_add_f32_dpp v132, v132, v132 row_mirror row_mask:0xf bank_mask:0xf bound_ctrl:1
	v_add_f32_dpp v133, v133, v133 row_mirror row_mask:0xf bank_mask:0xf bound_ctrl:1
	v_pk_fma_f32 v[16:17], v[24:25], v[132:133], v[16:17] op_sel_hi:[0,1,1]
	v_pk_fma_f32 v[12:13], v[24:25], v[132:133], v[12:13] op_sel:[1,0,0]
	v_pk_fma_f32 v[18:19], v[26:27], v[132:133], v[18:19] op_sel_hi:[0,1,1]
	v_pk_fma_f32 v[14:15], v[26:27], v[132:133], v[14:15] op_sel:[1,0,0]
	s_waitcnt lgkmcnt(1)
	v_pk_mul_f32 v[132:133], v[16:17], v[94:95] op_sel_hi:[1,0]
	v_pk_mul_f32 v[24:25], v[16:17], v[20:21] op_sel_hi:[1,0]
	v_pk_fma_f32 v[132:133], v[12:13], v[94:95], v[132:133] op_sel:[0,1,0]
	v_pk_fma_f32 v[24:25], v[12:13], v[20:21], v[24:25] op_sel:[0,1,0]
	v_pk_fma_f32 v[132:133], v[18:19], v[96:97], v[132:133] op_sel_hi:[1,0,1]
	v_pk_fma_f32 v[24:25], v[18:19], v[22:23], v[24:25] op_sel_hi:[1,0,1]
	v_pk_fma_f32 v[132:133], v[14:15], v[96:97], v[132:133] op_sel:[0,1,0]
	v_pk_fma_f32 v[24:25], v[14:15], v[22:23], v[24:25] op_sel:[0,1,0]
	v_cvt_pk_f16_f32 v96, v24, v25
	v_add_f32_dpp v132, v132, v132 quad_perm:[1,0,3,2] row_mask:0xf bank_mask:0xf bound_ctrl:1
	v_add_f32_dpp v133, v133, v133 quad_perm:[1,0,3,2] row_mask:0xf bank_mask:0xf bound_ctrl:1
	ds_read_b128 v[32:35], v114 offset:14848
	ds_read_b128 v[24:27], v114 offset:18944
	ds_read_b128 v[28:31], v114 offset:10752
	ds_read_b128 v[20:23], v114 offset:2560
	v_pk_fma_f32 v[16:17], v[120:121], v[130:131], v[16:17] op_sel_hi:[0,1,1]
	v_add_f32_dpp v132, v132, v132 quad_perm:[2,3,0,1] row_mask:0xf bank_mask:0xf bound_ctrl:1
	v_add_f32_dpp v133, v133, v133 quad_perm:[2,3,0,1] row_mask:0xf bank_mask:0xf bound_ctrl:1
	v_pk_fma_f32 v[12:13], v[120:121], v[130:131], v[12:13] op_sel:[1,0,0]
	v_add_f32_dpp v132, v132, v132 row_half_mirror row_mask:0xf bank_mask:0xf bound_ctrl:1
	v_add_f32_dpp v133, v133, v133 row_half_mirror row_mask:0xf bank_mask:0xf bound_ctrl:1
	v_pk_fma_f32 v[18:19], v[122:123], v[130:131], v[18:19] op_sel_hi:[0,1,1]
	v_pk_fma_f32 v[14:15], v[122:123], v[130:131], v[14:15] op_sel:[1,0,0]
	v_add_f32_dpp v132, v132, v132 row_mirror row_mask:0xf bank_mask:0xf bound_ctrl:1
	v_add_f32_dpp v133, v133, v133 row_mirror row_mask:0xf bank_mask:0xf bound_ctrl:1
	v_pk_fma_f32 v[16:17], v[116:117], v[132:133], v[16:17] op_sel_hi:[0,1,1]
	v_pk_fma_f32 v[12:13], v[116:117], v[132:133], v[12:13] op_sel:[1,0,0]
	v_pk_fma_f32 v[18:19], v[118:119], v[132:133], v[18:19] op_sel_hi:[0,1,1]
	v_pk_fma_f32 v[14:15], v[118:119], v[132:133], v[14:15] op_sel:[1,0,0]
	s_waitcnt lgkmcnt(0)
	v_pk_mul_f32 v[132:133], v[16:17], v[32:33] op_sel_hi:[1,0]
	v_pk_mul_f32 v[94:95], v[16:17], v[124:125] op_sel_hi:[1,0]
	v_pk_fma_f32 v[132:133], v[12:13], v[32:33], v[132:133] op_sel:[0,1,0]
	v_pk_fma_f32 v[94:95], v[12:13], v[124:125], v[94:95] op_sel:[0,1,0]
	v_pk_fma_f32 v[132:133], v[18:19], v[34:35], v[132:133] op_sel_hi:[1,0,1]
	v_pk_fma_f32 v[94:95], v[18:19], v[126:127], v[94:95] op_sel_hi:[1,0,1]
	v_pk_fma_f32 v[132:133], v[14:15], v[34:35], v[132:133] op_sel:[0,1,0]
	v_pk_fma_f32 v[94:95], v[14:15], v[126:127], v[94:95] op_sel:[0,1,0]
	v_cvt_pk_f16_f32 v94, v94, v95
	v_add_f32_dpp v132, v132, v132 quad_perm:[1,0,3,2] row_mask:0xf bank_mask:0xf bound_ctrl:1
	v_add_f32_dpp v133, v133, v133 quad_perm:[1,0,3,2] row_mask:0xf bank_mask:0xf bound_ctrl:1
	ds_write2st64_b32 v93, v96, v94 offset0:32 offset1:36
	ds_read_b128 v[94:97], v42 offset:14848
	ds_read_b128 v[116:119], v42 offset:18944
	ds_read_b128 v[120:123], v42 offset:10752
	ds_read_b128 v[124:127], v42 offset:2560
	ds_read_b64 v[130:131], v92 offset:1280
	v_pk_fma_f32 v[16:17], v[28:29], v[90:91], v[16:17] op_sel_hi:[0,1,1]
	v_add_f32_dpp v132, v132, v132 quad_perm:[2,3,0,1] row_mask:0xf bank_mask:0xf bound_ctrl:1
	v_add_f32_dpp v133, v133, v133 quad_perm:[2,3,0,1] row_mask:0xf bank_mask:0xf bound_ctrl:1
	v_pk_fma_f32 v[12:13], v[28:29], v[90:91], v[12:13] op_sel:[1,0,0]
	v_add_f32_dpp v132, v132, v132 row_half_mirror row_mask:0xf bank_mask:0xf bound_ctrl:1
	v_add_f32_dpp v133, v133, v133 row_half_mirror row_mask:0xf bank_mask:0xf bound_ctrl:1
	v_pk_fma_f32 v[18:19], v[30:31], v[90:91], v[18:19] op_sel_hi:[0,1,1]
	v_pk_fma_f32 v[14:15], v[30:31], v[90:91], v[14:15] op_sel:[1,0,0]
	ds_read_b64 v[90:91], v115 offset:22016
	v_add_f32_dpp v132, v132, v132 row_mirror row_mask:0xf bank_mask:0xf bound_ctrl:1
	v_add_f32_dpp v133, v133, v133 row_mirror row_mask:0xf bank_mask:0xf bound_ctrl:1
	v_pk_fma_f32 v[16:17], v[24:25], v[132:133], v[16:17] op_sel_hi:[0,1,1]
	v_pk_fma_f32 v[12:13], v[24:25], v[132:133], v[12:13] op_sel:[1,0,0]
	v_pk_fma_f32 v[18:19], v[26:27], v[132:133], v[18:19] op_sel_hi:[0,1,1]
	v_pk_fma_f32 v[14:15], v[26:27], v[132:133], v[14:15] op_sel:[1,0,0]
	s_waitcnt lgkmcnt(1)
	v_pk_mul_f32 v[132:133], v[16:17], v[94:95] op_sel_hi:[1,0]
	v_pk_mul_f32 v[24:25], v[16:17], v[20:21] op_sel_hi:[1,0]
	v_pk_fma_f32 v[132:133], v[12:13], v[94:95], v[132:133] op_sel:[0,1,0]
	v_pk_fma_f32 v[24:25], v[12:13], v[20:21], v[24:25] op_sel:[0,1,0]
	v_pk_fma_f32 v[132:133], v[18:19], v[96:97], v[132:133] op_sel_hi:[1,0,1]
	v_pk_fma_f32 v[24:25], v[18:19], v[22:23], v[24:25] op_sel_hi:[1,0,1]
	v_pk_fma_f32 v[132:133], v[14:15], v[96:97], v[132:133] op_sel:[0,1,0]
	v_pk_fma_f32 v[24:25], v[14:15], v[22:23], v[24:25] op_sel:[0,1,0]
	v_cvt_pk_f16_f32 v96, v24, v25
	v_add_f32_dpp v132, v132, v132 quad_perm:[1,0,3,2] row_mask:0xf bank_mask:0xf bound_ctrl:1
	v_add_f32_dpp v133, v133, v133 quad_perm:[1,0,3,2] row_mask:0xf bank_mask:0xf bound_ctrl:1
	ds_read_b128 v[32:35], v114 offset:15360
	ds_read_b128 v[24:27], v114 offset:19456
	ds_read_b128 v[28:31], v114 offset:11264
	ds_read_b128 v[20:23], v114 offset:3072
	v_pk_fma_f32 v[16:17], v[120:121], v[130:131], v[16:17] op_sel_hi:[0,1,1]
	v_add_f32_dpp v132, v132, v132 quad_perm:[2,3,0,1] row_mask:0xf bank_mask:0xf bound_ctrl:1
	v_add_f32_dpp v133, v133, v133 quad_perm:[2,3,0,1] row_mask:0xf bank_mask:0xf bound_ctrl:1
	v_pk_fma_f32 v[12:13], v[120:121], v[130:131], v[12:13] op_sel:[1,0,0]
	v_add_f32_dpp v132, v132, v132 row_half_mirror row_mask:0xf bank_mask:0xf bound_ctrl:1
	v_add_f32_dpp v133, v133, v133 row_half_mirror row_mask:0xf bank_mask:0xf bound_ctrl:1
	v_pk_fma_f32 v[18:19], v[122:123], v[130:131], v[18:19] op_sel_hi:[0,1,1]
	v_pk_fma_f32 v[14:15], v[122:123], v[130:131], v[14:15] op_sel:[1,0,0]
	v_add_f32_dpp v132, v132, v132 row_mirror row_mask:0xf bank_mask:0xf bound_ctrl:1
	v_add_f32_dpp v133, v133, v133 row_mirror row_mask:0xf bank_mask:0xf bound_ctrl:1
	v_pk_fma_f32 v[16:17], v[116:117], v[132:133], v[16:17] op_sel_hi:[0,1,1]
	v_pk_fma_f32 v[12:13], v[116:117], v[132:133], v[12:13] op_sel:[1,0,0]
	v_pk_fma_f32 v[18:19], v[118:119], v[132:133], v[18:19] op_sel_hi:[0,1,1]
	v_pk_fma_f32 v[14:15], v[118:119], v[132:133], v[14:15] op_sel:[1,0,0]
	s_waitcnt lgkmcnt(0)
	v_pk_mul_f32 v[132:133], v[16:17], v[32:33] op_sel_hi:[1,0]
	v_pk_mul_f32 v[94:95], v[16:17], v[124:125] op_sel_hi:[1,0]
	v_pk_fma_f32 v[132:133], v[12:13], v[32:33], v[132:133] op_sel:[0,1,0]
	v_pk_fma_f32 v[94:95], v[12:13], v[124:125], v[94:95] op_sel:[0,1,0]
	v_pk_fma_f32 v[132:133], v[18:19], v[34:35], v[132:133] op_sel_hi:[1,0,1]
	v_pk_fma_f32 v[94:95], v[18:19], v[126:127], v[94:95] op_sel_hi:[1,0,1]
	v_pk_fma_f32 v[132:133], v[14:15], v[34:35], v[132:133] op_sel:[0,1,0]
	v_pk_fma_f32 v[94:95], v[14:15], v[126:127], v[94:95] op_sel:[0,1,0]
	v_cvt_pk_f16_f32 v94, v94, v95
	v_add_f32_dpp v132, v132, v132 quad_perm:[1,0,3,2] row_mask:0xf bank_mask:0xf bound_ctrl:1
	v_add_f32_dpp v133, v133, v133 quad_perm:[1,0,3,2] row_mask:0xf bank_mask:0xf bound_ctrl:1
	ds_write2st64_b32 v93, v96, v94 offset0:40 offset1:44
	ds_read_b128 v[94:97], v42 offset:15360
	ds_read_b128 v[116:119], v42 offset:19456
	ds_read_b128 v[120:123], v42 offset:11264
	ds_read_b128 v[124:127], v42 offset:3072
	ds_read_b64 v[130:131], v92 offset:1536
	v_pk_fma_f32 v[16:17], v[28:29], v[90:91], v[16:17] op_sel_hi:[0,1,1]
	v_add_f32_dpp v132, v132, v132 quad_perm:[2,3,0,1] row_mask:0xf bank_mask:0xf bound_ctrl:1
	v_add_f32_dpp v133, v133, v133 quad_perm:[2,3,0,1] row_mask:0xf bank_mask:0xf bound_ctrl:1
	v_pk_fma_f32 v[12:13], v[28:29], v[90:91], v[12:13] op_sel:[1,0,0]
	v_add_f32_dpp v132, v132, v132 row_half_mirror row_mask:0xf bank_mask:0xf bound_ctrl:1
	v_add_f32_dpp v133, v133, v133 row_half_mirror row_mask:0xf bank_mask:0xf bound_ctrl:1
	v_pk_fma_f32 v[18:19], v[30:31], v[90:91], v[18:19] op_sel_hi:[0,1,1]
	v_pk_fma_f32 v[14:15], v[30:31], v[90:91], v[14:15] op_sel:[1,0,0]
	ds_read_b64 v[90:91], v115 offset:22272
	v_add_f32_dpp v132, v132, v132 row_mirror row_mask:0xf bank_mask:0xf bound_ctrl:1
	v_add_f32_dpp v133, v133, v133 row_mirror row_mask:0xf bank_mask:0xf bound_ctrl:1
	v_pk_fma_f32 v[16:17], v[24:25], v[132:133], v[16:17] op_sel_hi:[0,1,1]
	v_pk_fma_f32 v[12:13], v[24:25], v[132:133], v[12:13] op_sel:[1,0,0]
	v_pk_fma_f32 v[18:19], v[26:27], v[132:133], v[18:19] op_sel_hi:[0,1,1]
	v_pk_fma_f32 v[14:15], v[26:27], v[132:133], v[14:15] op_sel:[1,0,0]
	s_waitcnt lgkmcnt(1)
	v_pk_mul_f32 v[132:133], v[16:17], v[94:95] op_sel_hi:[1,0]
	v_pk_mul_f32 v[24:25], v[16:17], v[20:21] op_sel_hi:[1,0]
	v_pk_fma_f32 v[132:133], v[12:13], v[94:95], v[132:133] op_sel:[0,1,0]
	v_pk_fma_f32 v[24:25], v[12:13], v[20:21], v[24:25] op_sel:[0,1,0]
	v_pk_fma_f32 v[132:133], v[18:19], v[96:97], v[132:133] op_sel_hi:[1,0,1]
	v_pk_fma_f32 v[24:25], v[18:19], v[22:23], v[24:25] op_sel_hi:[1,0,1]
	v_pk_fma_f32 v[132:133], v[14:15], v[96:97], v[132:133] op_sel:[0,1,0]
	v_pk_fma_f32 v[24:25], v[14:15], v[22:23], v[24:25] op_sel:[0,1,0]
	v_cvt_pk_f16_f32 v96, v24, v25
	v_add_f32_dpp v132, v132, v132 quad_perm:[1,0,3,2] row_mask:0xf bank_mask:0xf bound_ctrl:1
	v_add_f32_dpp v133, v133, v133 quad_perm:[1,0,3,2] row_mask:0xf bank_mask:0xf bound_ctrl:1
	ds_read_b128 v[32:35], v114 offset:15872
	ds_read_b128 v[24:27], v114 offset:19968
	ds_read_b128 v[28:31], v114 offset:11776
	ds_read_b128 v[20:23], v114 offset:3584
	v_pk_fma_f32 v[16:17], v[120:121], v[130:131], v[16:17] op_sel_hi:[0,1,1]
	v_add_f32_dpp v132, v132, v132 quad_perm:[2,3,0,1] row_mask:0xf bank_mask:0xf bound_ctrl:1
	v_add_f32_dpp v133, v133, v133 quad_perm:[2,3,0,1] row_mask:0xf bank_mask:0xf bound_ctrl:1
	v_pk_fma_f32 v[12:13], v[120:121], v[130:131], v[12:13] op_sel:[1,0,0]
	v_add_f32_dpp v132, v132, v132 row_half_mirror row_mask:0xf bank_mask:0xf bound_ctrl:1
	v_add_f32_dpp v133, v133, v133 row_half_mirror row_mask:0xf bank_mask:0xf bound_ctrl:1
	v_pk_fma_f32 v[18:19], v[122:123], v[130:131], v[18:19] op_sel_hi:[0,1,1]
	v_pk_fma_f32 v[14:15], v[122:123], v[130:131], v[14:15] op_sel:[1,0,0]
	v_add_f32_dpp v132, v132, v132 row_mirror row_mask:0xf bank_mask:0xf bound_ctrl:1
	v_add_f32_dpp v133, v133, v133 row_mirror row_mask:0xf bank_mask:0xf bound_ctrl:1
	v_pk_fma_f32 v[16:17], v[116:117], v[132:133], v[16:17] op_sel_hi:[0,1,1]
	v_pk_fma_f32 v[12:13], v[116:117], v[132:133], v[12:13] op_sel:[1,0,0]
	v_pk_fma_f32 v[18:19], v[118:119], v[132:133], v[18:19] op_sel_hi:[0,1,1]
	v_pk_fma_f32 v[14:15], v[118:119], v[132:133], v[14:15] op_sel:[1,0,0]
	s_waitcnt lgkmcnt(0)
	v_pk_mul_f32 v[132:133], v[16:17], v[32:33] op_sel_hi:[1,0]
	v_pk_mul_f32 v[94:95], v[16:17], v[124:125] op_sel_hi:[1,0]
	v_pk_fma_f32 v[132:133], v[12:13], v[32:33], v[132:133] op_sel:[0,1,0]
	v_pk_fma_f32 v[94:95], v[12:13], v[124:125], v[94:95] op_sel:[0,1,0]
	v_pk_fma_f32 v[132:133], v[18:19], v[34:35], v[132:133] op_sel_hi:[1,0,1]
	v_pk_fma_f32 v[94:95], v[18:19], v[126:127], v[94:95] op_sel_hi:[1,0,1]
	v_pk_fma_f32 v[132:133], v[14:15], v[34:35], v[132:133] op_sel:[0,1,0]
	v_pk_fma_f32 v[94:95], v[14:15], v[126:127], v[94:95] op_sel:[0,1,0]
	v_cvt_pk_f16_f32 v94, v94, v95
	v_add_f32_dpp v132, v132, v132 quad_perm:[1,0,3,2] row_mask:0xf bank_mask:0xf bound_ctrl:1
	v_add_f32_dpp v133, v133, v133 quad_perm:[1,0,3,2] row_mask:0xf bank_mask:0xf bound_ctrl:1
	ds_write2st64_b32 v93, v96, v94 offset0:48 offset1:52
	ds_read_b128 v[94:97], v42 offset:15872
	ds_read_b128 v[116:119], v42 offset:19968
	ds_read_b128 v[120:123], v42 offset:11776
	ds_read_b128 v[124:127], v42 offset:3584
	ds_read_b64 v[130:131], v92 offset:1792
	v_pk_fma_f32 v[16:17], v[28:29], v[90:91], v[16:17] op_sel_hi:[0,1,1]
	v_add_f32_dpp v132, v132, v132 quad_perm:[2,3,0,1] row_mask:0xf bank_mask:0xf bound_ctrl:1
	v_add_f32_dpp v133, v133, v133 quad_perm:[2,3,0,1] row_mask:0xf bank_mask:0xf bound_ctrl:1
	v_pk_fma_f32 v[12:13], v[28:29], v[90:91], v[12:13] op_sel:[1,0,0]
	v_add_f32_dpp v132, v132, v132 row_half_mirror row_mask:0xf bank_mask:0xf bound_ctrl:1
	v_add_f32_dpp v133, v133, v133 row_half_mirror row_mask:0xf bank_mask:0xf bound_ctrl:1
	v_pk_fma_f32 v[18:19], v[30:31], v[90:91], v[18:19] op_sel_hi:[0,1,1]
	v_pk_fma_f32 v[14:15], v[30:31], v[90:91], v[14:15] op_sel:[1,0,0]
	ds_read_b64 v[90:91], v115 offset:22272
	v_add_f32_dpp v132, v132, v132 row_mirror row_mask:0xf bank_mask:0xf bound_ctrl:1
	v_add_f32_dpp v133, v133, v133 row_mirror row_mask:0xf bank_mask:0xf bound_ctrl:1
	v_pk_fma_f32 v[16:17], v[24:25], v[132:133], v[16:17] op_sel_hi:[0,1,1]
	v_pk_fma_f32 v[12:13], v[24:25], v[132:133], v[12:13] op_sel:[1,0,0]
	v_pk_fma_f32 v[18:19], v[26:27], v[132:133], v[18:19] op_sel_hi:[0,1,1]
	v_pk_fma_f32 v[14:15], v[26:27], v[132:133], v[14:15] op_sel:[1,0,0]
	s_waitcnt lgkmcnt(1)
	v_pk_mul_f32 v[132:133], v[16:17], v[94:95] op_sel_hi:[1,0]
	v_pk_mul_f32 v[24:25], v[16:17], v[20:21] op_sel_hi:[1,0]
	v_pk_fma_f32 v[132:133], v[12:13], v[94:95], v[132:133] op_sel:[0,1,0]
	v_pk_fma_f32 v[24:25], v[12:13], v[20:21], v[24:25] op_sel:[0,1,0]
	v_pk_fma_f32 v[132:133], v[18:19], v[96:97], v[132:133] op_sel_hi:[1,0,1]
	v_pk_fma_f32 v[24:25], v[18:19], v[22:23], v[24:25] op_sel_hi:[1,0,1]
	v_pk_fma_f32 v[132:133], v[14:15], v[96:97], v[132:133] op_sel:[0,1,0]
	v_pk_fma_f32 v[24:25], v[14:15], v[22:23], v[24:25] op_sel:[0,1,0]
	v_cvt_pk_f16_f32 v96, v24, v25
	v_add_f32_dpp v132, v132, v132 quad_perm:[1,0,3,2] row_mask:0xf bank_mask:0xf bound_ctrl:1
	v_add_f32_dpp v133, v133, v133 quad_perm:[1,0,3,2] row_mask:0xf bank_mask:0xf bound_ctrl:1
	ds_read_b128 v[32:35], v114 offset:15872
	ds_read_b128 v[24:27], v114 offset:19968
	ds_read_b128 v[28:31], v114 offset:11776
	ds_read_b128 v[20:23], v114 offset:3584
	v_pk_fma_f32 v[16:17], v[120:121], v[130:131], v[16:17] op_sel_hi:[0,1,1]
	v_add_f32_dpp v132, v132, v132 quad_perm:[2,3,0,1] row_mask:0xf bank_mask:0xf bound_ctrl:1
	v_add_f32_dpp v133, v133, v133 quad_perm:[2,3,0,1] row_mask:0xf bank_mask:0xf bound_ctrl:1
	v_pk_fma_f32 v[12:13], v[120:121], v[130:131], v[12:13] op_sel:[1,0,0]
	v_add_f32_dpp v132, v132, v132 row_half_mirror row_mask:0xf bank_mask:0xf bound_ctrl:1
	v_add_f32_dpp v133, v133, v133 row_half_mirror row_mask:0xf bank_mask:0xf bound_ctrl:1
	v_pk_fma_f32 v[18:19], v[122:123], v[130:131], v[18:19] op_sel_hi:[0,1,1]
	v_pk_fma_f32 v[14:15], v[122:123], v[130:131], v[14:15] op_sel:[1,0,0]
	v_add_f32_dpp v132, v132, v132 row_mirror row_mask:0xf bank_mask:0xf bound_ctrl:1
	v_add_f32_dpp v133, v133, v133 row_mirror row_mask:0xf bank_mask:0xf bound_ctrl:1
	v_pk_fma_f32 v[16:17], v[116:117], v[132:133], v[16:17] op_sel_hi:[0,1,1]
	v_pk_fma_f32 v[12:13], v[116:117], v[132:133], v[12:13] op_sel:[1,0,0]
	v_pk_fma_f32 v[18:19], v[118:119], v[132:133], v[18:19] op_sel_hi:[0,1,1]
	v_pk_fma_f32 v[14:15], v[118:119], v[132:133], v[14:15] op_sel:[1,0,0]
	v_pk_mul_f32 v[94:95], v[16:17], v[124:125] op_sel_hi:[1,0]
	v_pk_fma_f32 v[94:95], v[12:13], v[124:125], v[94:95] op_sel:[0,1,0]
	v_pk_fma_f32 v[94:95], v[18:19], v[126:127], v[94:95] op_sel_hi:[1,0,1]
	v_pk_fma_f32 v[94:95], v[14:15], v[126:127], v[94:95] op_sel:[0,1,0]
	v_cvt_pk_f16_f32 v94, v94, v95
	ds_write2st64_b32 v93, v96, v94 offset0:56 offset1:60
	s_waitcnt vmcnt(10) lgkmcnt(1)
	v_cvt_f32_f16_sdwa v91, v60 dst_sel:DWORD dst_unused:UNUSED_PAD src0_sel:WORD_1
	v_cvt_f32_f16_e32 v90, v60
	v_cvt_f32_f16_sdwa v93, v61 dst_sel:DWORD dst_unused:UNUSED_PAD src0_sel:WORD_1
	v_cvt_f32_f16_e32 v92, v61
	s_waitcnt vmcnt(7)
	v_cvt_f32_f16_sdwa v25, v68 dst_sel:DWORD dst_unused:UNUSED_PAD src0_sel:WORD_1
	v_cvt_f32_f16_e32 v24, v68
	v_cvt_f32_f16_sdwa v27, v69 dst_sel:DWORD dst_unused:UNUSED_PAD src0_sel:WORD_1
	v_cvt_f32_f16_e32 v26, v69
	v_pk_mul_f32 v[30:31], v[0:1], v[90:91]
	v_pk_mul_f32 v[28:29], v[2:3], v[92:93]
	v_pk_mul_f32 v[96:97], v[30:31], v[30:31]
	v_pk_mul_f32 v[94:95], v[28:29], v[28:29]
	v_add_f32_e32 v42, v96, v97
	v_cvt_f32_f16_sdwa v33, v58 dst_sel:DWORD dst_unused:UNUSED_PAD src0_sel:WORD_1
	v_cvt_f32_f16_e32 v32, v58
	v_cvt_f32_f16_sdwa v35, v59 dst_sel:DWORD dst_unused:UNUSED_PAD src0_sel:WORD_1
	v_cvt_f32_f16_e32 v34, v59
	v_add_f32_e32 v42, v94, v42
	v_add_f32_e32 v42, v95, v42
	v_pk_add_f32 v[94:95], v[24:25], -1.0 op_sel_hi:[1,0]
	v_pk_add_f32 v[96:97], v[26:27], -1.0 op_sel_hi:[1,0]
	v_pk_fma_f32 v[94:95], v[4:5], v[94:95], 1.0 op_sel_hi:[1,1,0]
	v_pk_fma_f32 v[96:97], v[6:7], v[96:97], 1.0 op_sel_hi:[1,1,0]
	v_pk_mul_f32 v[94:95], v[90:91], v[94:95]
	v_pk_mul_f32 v[96:97], v[92:93], v[96:97]
	v_pk_mul_f32 v[90:91], v[32:33], v[94:95]
	v_pk_mul_f32 v[92:93], v[34:35], v[96:97]
	v_pk_mul_f32 v[90:91], v[8:9], v[90:91]
	v_pk_mul_f32 v[92:93], v[10:11], v[92:93]
	v_add_f32_e32 v90, v90, v91
	v_add_f32_e32 v91, v92, v93
	ds_read_b128 v[20:23], v114 offset:7936
	v_add_f32_e32 v90, v90, v91
	v_add_f32_dpp v42, v42, v42 quad_perm:[1,0,3,2] row_mask:0xf bank_mask:0xf bound_ctrl:1
	s_nop 0
	v_add_f32_dpp v90, v90, v90 quad_perm:[1,0,3,2] row_mask:0xf bank_mask:0xf bound_ctrl:1
	v_add_f32_dpp v42, v42, v42 quad_perm:[2,3,0,1] row_mask:0xf bank_mask:0xf bound_ctrl:1
	s_nop 0
	v_add_f32_dpp v90, v90, v90 quad_perm:[2,3,0,1] row_mask:0xf bank_mask:0xf bound_ctrl:1
	v_add_f32_dpp v42, v42, v42 row_half_mirror row_mask:0xf bank_mask:0xf bound_ctrl:1
	s_nop 0
	v_add_f32_dpp v90, v90, v90 row_half_mirror row_mask:0xf bank_mask:0xf bound_ctrl:1
	v_mov_b32_dpp v116, v42 row_mirror row_mask:0xf bank_mask:0xf bound_ctrl:1
	s_nop 0
	v_mov_b32_dpp v91, v90 row_mirror row_mask:0xf bank_mask:0xf bound_ctrl:1
	s_and_saveexec_b64 s[12:13], s[6:7]
	s_cbranch_execz .LBB0_419
	s_add_i32 s50, s94, 16
	v_cmp_lt_u32_e32 vcc, s50, v106
	s_and_b64 exec, exec, vcc
	s_cbranch_execz .LBB0_419
	v_add_f32_e32 v92, v90, v91
	v_add_u32_e32 v90, s50, v46
	v_ashrrev_i32_e32 v91, 31, v90
	v_lshlrev_b64 v[90:91], 6, v[90:91]
	v_lshl_add_u64 v[90:91], s[58:59], 0, v[90:91]
	global_store_dword v[90:91], v92, off

.LBB0_425:
	s_or_b64 exec, exec, s[12:13]
	s_and_b32 s12, s96, 1
	s_mulk_i32 s12, 0x5800
	v_pk_mul_f32 v[34:35], v[12:13], v[20:21] op_sel:[0,1]
	v_cndmask_b32_e64 v12, 0, 1, s[64:65]
	v_lshl_add_u32 v42, v12, 14, v109
	v_mul_lo_u32 v12, v12, s88
	v_lshl_or_b32 v95, v37, 2, s12
	v_pk_mul_f32 v[28:29], v[16:17], v[20:21] op_sel_hi:[1,0]
	v_pk_mul_f32 v[32:33], v[18:19], v[22:23] op_sel_hi:[1,0]
	v_pk_mul_f32 v[90:91], v[14:15], v[22:23] op_sel:[0,1]
	v_add_u32_e32 v92, v110, v12
	v_or_b32_e32 v93, v111, v12
	v_lshl_or_b32 v94, v36, 2, s12
	ds_read_b64 v[30:31], v95 offset:20480
	ds_read_b128 v[12:15], v94
	ds_read_b128 v[20:23], v94 offset:8192
	ds_read_b128 v[16:19], v94 offset:16384
	ds_read_b128 v[24:27], v94 offset:12288
	s_mov_b32 s12, 0
.LBB0_426:
	s_waitcnt lgkmcnt(0)
	v_pk_mul_f32 v[134:135], v[28:29], v[24:25] op_sel_hi:[1,0]
	v_pk_fma_f32 v[134:135], v[34:35], v[24:25], v[134:135] op_sel:[0,1,0]
	v_pk_fma_f32 v[134:135], v[32:33], v[26:27], v[134:135] op_sel_hi:[1,0,1]
	v_pk_fma_f32 v[134:135], v[90:91], v[26:27], v[134:135] op_sel:[0,1,0]
	ds_read_b128 v[116:119], v93 offset:12288
	ds_read_b128 v[120:123], v93 offset:16384
	ds_read_b128 v[124:127], v93 offset:8192
	ds_read_b128 v[130:133], v93
	ds_read_b64 v[96:97], v92
	v_pk_fma_f32 v[28:29], v[20:21], v[30:31], v[28:29] op_sel_hi:[0,1,1]
	v_pk_fma_f32 v[34:35], v[20:21], v[30:31], v[34:35] op_sel:[1,0,0]
	v_add_f32_dpp v134, v134, v134 quad_perm:[1,0,3,2] row_mask:0xf bank_mask:0xf bound_ctrl:1
	v_add_f32_dpp v135, v135, v135 quad_perm:[1,0,3,2] row_mask:0xf bank_mask:0xf bound_ctrl:1
	v_pk_fma_f32 v[32:33], v[22:23], v[30:31], v[32:33] op_sel_hi:[0,1,1]
	v_add_f32_dpp v134, v134, v134 quad_perm:[2,3,0,1] row_mask:0xf bank_mask:0xf bound_ctrl:1
	v_add_f32_dpp v135, v135, v135 quad_perm:[2,3,0,1] row_mask:0xf bank_mask:0xf bound_ctrl:1
	v_pk_fma_f32 v[90:91], v[22:23], v[30:31], v[90:91] op_sel:[1,0,0]
	v_add_f32_dpp v134, v134, v134 row_half_mirror row_mask:0xf bank_mask:0xf bound_ctrl:1
	v_add_f32_dpp v135, v135, v135 row_half_mirror row_mask:0xf bank_mask:0xf bound_ctrl:1
	ds_read_b64 v[30:31], v95 offset:20736
	v_add_f32_dpp v134, v134, v134 row_mirror row_mask:0xf bank_mask:0xf bound_ctrl:1
	v_add_f32_dpp v135, v135, v135 row_mirror row_mask:0xf bank_mask:0xf bound_ctrl:1
	v_pk_fma_f32 v[28:29], v[16:17], v[134:135], v[28:29] op_sel_hi:[0,1,1]
	v_pk_fma_f32 v[34:35], v[16:17], v[134:135], v[34:35] op_sel:[1,0,0]
	v_pk_fma_f32 v[32:33], v[18:19], v[134:135], v[32:33] op_sel_hi:[0,1,1]
	v_pk_fma_f32 v[90:91], v[18:19], v[134:135], v[90:91] op_sel:[1,0,0]
	s_waitcnt lgkmcnt(1)
	v_pk_mul_f32 v[134:135], v[28:29], v[116:117] op_sel_hi:[1,0]
	v_pk_mul_f32 v[16:17], v[28:29], v[12:13] op_sel_hi:[1,0]
	v_pk_fma_f32 v[134:135], v[34:35], v[116:117], v[134:135] op_sel:[0,1,0]
	v_pk_fma_f32 v[16:17], v[34:35], v[12:13], v[16:17] op_sel:[0,1,0]
	v_pk_fma_f32 v[134:135], v[32:33], v[118:119], v[134:135] op_sel_hi:[1,0,1]
	v_pk_fma_f32 v[16:17], v[32:33], v[14:15], v[16:17] op_sel_hi:[1,0,1]
	v_pk_fma_f32 v[134:135], v[90:91], v[118:119], v[134:135] op_sel:[0,1,0]
	v_pk_fma_f32 v[16:17], v[90:91], v[14:15], v[16:17] op_sel:[0,1,0]
	v_cvt_pk_f16_f32 v118, v16, v17
	v_add_f32_dpp v134, v134, v134 quad_perm:[1,0,3,2] row_mask:0xf bank_mask:0xf bound_ctrl:1
	v_add_f32_dpp v135, v135, v135 quad_perm:[1,0,3,2] row_mask:0xf bank_mask:0xf bound_ctrl:1
	ds_read_b128 v[24:27], v94 offset:12800
	ds_read_b128 v[16:19], v94 offset:16896
	ds_read_b128 v[20:23], v94 offset:8704
	ds_read_b128 v[12:15], v94 offset:512
	v_pk_fma_f32 v[28:29], v[124:125], v[96:97], v[28:29] op_sel_hi:[0,1,1]
	v_add_f32_dpp v134, v134, v134 quad_perm:[2,3,0,1] row_mask:0xf bank_mask:0xf bound_ctrl:1
	v_add_f32_dpp v135, v135, v135 quad_perm:[2,3,0,1] row_mask:0xf bank_mask:0xf bound_ctrl:1
	v_pk_fma_f32 v[34:35], v[124:125], v[96:97], v[34:35] op_sel:[1,0,0]
	v_add_f32_dpp v134, v134, v134 row_half_mirror row_mask:0xf bank_mask:0xf bound_ctrl:1
	v_add_f32_dpp v135, v135, v135 row_half_mirror row_mask:0xf bank_mask:0xf bound_ctrl:1
	v_pk_fma_f32 v[32:33], v[126:127], v[96:97], v[32:33] op_sel_hi:[0,1,1]
	v_pk_fma_f32 v[90:91], v[126:127], v[96:97], v[90:91] op_sel:[1,0,0]
	v_add_f32_dpp v134, v134, v134 row_mirror row_mask:0xf bank_mask:0xf bound_ctrl:1
	v_add_f32_dpp v135, v135, v135 row_mirror row_mask:0xf bank_mask:0xf bound_ctrl:1
	v_pk_fma_f32 v[28:29], v[120:121], v[134:135], v[28:29] op_sel_hi:[0,1,1]
	v_pk_fma_f32 v[34:35], v[120:121], v[134:135], v[34:35] op_sel:[1,0,0]
	v_pk_fma_f32 v[32:33], v[122:123], v[134:135], v[32:33] op_sel_hi:[0,1,1]
	v_pk_fma_f32 v[90:91], v[122:123], v[134:135], v[90:91] op_sel:[1,0,0]
	s_waitcnt lgkmcnt(0)
	v_pk_mul_f32 v[134:135], v[28:29], v[24:25] op_sel_hi:[1,0]
	v_pk_mul_f32 v[116:117], v[28:29], v[130:131] op_sel_hi:[1,0]
	v_pk_fma_f32 v[134:135], v[34:35], v[24:25], v[134:135] op_sel:[0,1,0]
	v_pk_fma_f32 v[116:117], v[34:35], v[130:131], v[116:117] op_sel:[0,1,0]
	v_pk_fma_f32 v[134:135], v[32:33], v[26:27], v[134:135] op_sel_hi:[1,0,1]
	v_pk_fma_f32 v[116:117], v[32:33], v[132:133], v[116:117] op_sel_hi:[1,0,1]
	v_pk_fma_f32 v[134:135], v[90:91], v[26:27], v[134:135] op_sel:[0,1,0]
	v_pk_fma_f32 v[116:117], v[90:91], v[132:133], v[116:117] op_sel:[0,1,0]
	v_cvt_pk_f16_f32 v116, v116, v117
	v_add_f32_dpp v134, v134, v134 quad_perm:[1,0,3,2] row_mask:0xf bank_mask:0xf bound_ctrl:1
	v_add_f32_dpp v135, v135, v135 quad_perm:[1,0,3,2] row_mask:0xf bank_mask:0xf bound_ctrl:1
	ds_write2st64_b32 v42, v118, v116 offset0:0 offset1:4
	ds_read_b128 v[116:119], v93 offset:12800
	ds_read_b128 v[120:123], v93 offset:16896
	ds_read_b128 v[124:127], v93 offset:8704
	ds_read_b128 v[130:133], v93 offset:512
	ds_read_b64 v[96:97], v92 offset:256
	v_pk_fma_f32 v[28:29], v[20:21], v[30:31], v[28:29] op_sel_hi:[0,1,1]
	v_add_f32_dpp v134, v134, v134 quad_perm:[2,3,0,1] row_mask:0xf bank_mask:0xf bound_ctrl:1
	v_add_f32_dpp v135, v135, v135 quad_perm:[2,3,0,1] row_mask:0xf bank_mask:0xf bound_ctrl:1
	v_pk_fma_f32 v[34:35], v[20:21], v[30:31], v[34:35] op_sel:[1,0,0]
	v_add_f32_dpp v134, v134, v134 row_half_mirror row_mask:0xf bank_mask:0xf bound_ctrl:1
	v_add_f32_dpp v135, v135, v135 row_half_mirror row_mask:0xf bank_mask:0xf bound_ctrl:1
	v_pk_fma_f32 v[32:33], v[22:23], v[30:31], v[32:33] op_sel_hi:[0,1,1]
	v_pk_fma_f32 v[90:91], v[22:23], v[30:31], v[90:91] op_sel:[1,0,0]
	ds_read_b64 v[30:31], v95 offset:20992
	v_add_f32_dpp v134, v134, v134 row_mirror row_mask:0xf bank_mask:0xf bound_ctrl:1
	v_add_f32_dpp v135, v135, v135 row_mirror row_mask:0xf bank_mask:0xf bound_ctrl:1
	v_pk_fma_f32 v[28:29], v[16:17], v[134:135], v[28:29] op_sel_hi:[0,1,1]
	v_pk_fma_f32 v[34:35], v[16:17], v[134:135], v[34:35] op_sel:[1,0,0]
	v_pk_fma_f32 v[32:33], v[18:19], v[134:135], v[32:33] op_sel_hi:[0,1,1]
	v_pk_fma_f32 v[90:91], v[18:19], v[134:135], v[90:91] op_sel:[1,0,0]
	s_waitcnt lgkmcnt(1)
	v_pk_mul_f32 v[134:135], v[28:29], v[116:117] op_sel_hi:[1,0]
	v_pk_mul_f32 v[16:17], v[28:29], v[12:13] op_sel_hi:[1,0]
	v_pk_fma_f32 v[134:135], v[34:35], v[116:117], v[134:135] op_sel:[0,1,0]
	v_pk_fma_f32 v[16:17], v[34:35], v[12:13], v[16:17] op_sel:[0,1,0]
	v_pk_fma_f32 v[134:135], v[32:33], v[118:119], v[134:135] op_sel_hi:[1,0,1]
	v_pk_fma_f32 v[16:17], v[32:33], v[14:15], v[16:17] op_sel_hi:[1,0,1]
	v_pk_fma_f32 v[134:135], v[90:91], v[118:119], v[134:135] op_sel:[0,1,0]
	v_pk_fma_f32 v[16:17], v[90:91], v[14:15], v[16:17] op_sel:[0,1,0]
	v_cvt_pk_f16_f32 v118, v16, v17
	v_add_f32_dpp v134, v134, v134 quad_perm:[1,0,3,2] row_mask:0xf bank_mask:0xf bound_ctrl:1
	v_add_f32_dpp v135, v135, v135 quad_perm:[1,0,3,2] row_mask:0xf bank_mask:0xf bound_ctrl:1
	ds_read_b128 v[24:27], v94 offset:13312
	ds_read_b128 v[16:19], v94 offset:17408
	ds_read_b128 v[20:23], v94 offset:9216
	ds_read_b128 v[12:15], v94 offset:1024
	v_pk_fma_f32 v[28:29], v[124:125], v[96:97], v[28:29] op_sel_hi:[0,1,1]
	v_add_f32_dpp v134, v134, v134 quad_perm:[2,3,0,1] row_mask:0xf bank_mask:0xf bound_ctrl:1
	v_add_f32_dpp v135, v135, v135 quad_perm:[2,3,0,1] row_mask:0xf bank_mask:0xf bound_ctrl:1
	v_pk_fma_f32 v[34:35], v[124:125], v[96:97], v[34:35] op_sel:[1,0,0]
	v_add_f32_dpp v134, v134, v134 row_half_mirror row_mask:0xf bank_mask:0xf bound_ctrl:1
	v_add_f32_dpp v135, v135, v135 row_half_mirror row_mask:0xf bank_mask:0xf bound_ctrl:1
	v_pk_fma_f32 v[32:33], v[126:127], v[96:97], v[32:33] op_sel_hi:[0,1,1]
	v_pk_fma_f32 v[90:91], v[126:127], v[96:97], v[90:91] op_sel:[1,0,0]
	v_add_f32_dpp v134, v134, v134 row_mirror row_mask:0xf bank_mask:0xf bound_ctrl:1
	v_add_f32_dpp v135, v135, v135 row_mirror row_mask:0xf bank_mask:0xf bound_ctrl:1
	v_pk_fma_f32 v[28:29], v[120:121], v[134:135], v[28:29] op_sel_hi:[0,1,1]
	v_pk_fma_f32 v[34:35], v[120:121], v[134:135], v[34:35] op_sel:[1,0,0]
	v_pk_fma_f32 v[32:33], v[122:123], v[134:135], v[32:33] op_sel_hi:[0,1,1]
	v_pk_fma_f32 v[90:91], v[122:123], v[134:135], v[90:91] op_sel:[1,0,0]
	s_waitcnt lgkmcnt(0)
	v_pk_mul_f32 v[134:135], v[28:29], v[24:25] op_sel_hi:[1,0]
	v_pk_mul_f32 v[116:117], v[28:29], v[130:131] op_sel_hi:[1,0]
	v_pk_fma_f32 v[134:135], v[34:35], v[24:25], v[134:135] op_sel:[0,1,0]
	v_pk_fma_f32 v[116:117], v[34:35], v[130:131], v[116:117] op_sel:[0,1,0]
	v_pk_fma_f32 v[134:135], v[32:33], v[26:27], v[134:135] op_sel_hi:[1,0,1]
	v_pk_fma_f32 v[116:117], v[32:33], v[132:133], v[116:117] op_sel_hi:[1,0,1]
	v_pk_fma_f32 v[134:135], v[90:91], v[26:27], v[134:135] op_sel:[0,1,0]
	v_pk_fma_f32 v[116:117], v[90:91], v[132:133], v[116:117] op_sel:[0,1,0]
	v_cvt_pk_f16_f32 v116, v116, v117
	v_add_f32_dpp v134, v134, v134 quad_perm:[1,0,3,2] row_mask:0xf bank_mask:0xf bound_ctrl:1
	v_add_f32_dpp v135, v135, v135 quad_perm:[1,0,3,2] row_mask:0xf bank_mask:0xf bound_ctrl:1
	ds_write2st64_b32 v42, v118, v116 offset0:8 offset1:12
	ds_read_b128 v[116:119], v93 offset:13312
	ds_read_b128 v[120:123], v93 offset:17408
	ds_read_b128 v[124:127], v93 offset:9216
	ds_read_b128 v[130:133], v93 offset:1024
	ds_read_b64 v[96:97], v92 offset:512
	v_pk_fma_f32 v[28:29], v[20:21], v[30:31], v[28:29] op_sel_hi:[0,1,1]
	v_add_f32_dpp v134, v134, v134 quad_perm:[2,3,0,1] row_mask:0xf bank_mask:0xf bound_ctrl:1
	v_add_f32_dpp v135, v135, v135 quad_perm:[2,3,0,1] row_mask:0xf bank_mask:0xf bound_ctrl:1
	v_pk_fma_f32 v[34:35], v[20:21], v[30:31], v[34:35] op_sel:[1,0,0]
	v_add_f32_dpp v134, v134, v134 row_half_mirror row_mask:0xf bank_mask:0xf bound_ctrl:1
	v_add_f32_dpp v135, v135, v135 row_half_mirror row_mask:0xf bank_mask:0xf bound_ctrl:1
	v_pk_fma_f32 v[32:33], v[22:23], v[30:31], v[32:33] op_sel_hi:[0,1,1]
	v_pk_fma_f32 v[90:91], v[22:23], v[30:31], v[90:91] op_sel:[1,0,0]
	ds_read_b64 v[30:31], v95 offset:21248
	v_add_f32_dpp v134, v134, v134 row_mirror row_mask:0xf bank_mask:0xf bound_ctrl:1
	v_add_f32_dpp v135, v135, v135 row_mirror row_mask:0xf bank_mask:0xf bound_ctrl:1
	v_pk_fma_f32 v[28:29], v[16:17], v[134:135], v[28:29] op_sel_hi:[0,1,1]
	v_pk_fma_f32 v[34:35], v[16:17], v[134:135], v[34:35] op_sel:[1,0,0]
	v_pk_fma_f32 v[32:33], v[18:19], v[134:135], v[32:33] op_sel_hi:[0,1,1]
	v_pk_fma_f32 v[90:91], v[18:19], v[134:135], v[90:91] op_sel:[1,0,0]
	s_waitcnt lgkmcnt(1)
	v_pk_mul_f32 v[134:135], v[28:29], v[116:117] op_sel_hi:[1,0]
	v_pk_mul_f32 v[16:17], v[28:29], v[12:13] op_sel_hi:[1,0]
	v_pk_fma_f32 v[134:135], v[34:35], v[116:117], v[134:135] op_sel:[0,1,0]
	v_pk_fma_f32 v[16:17], v[34:35], v[12:13], v[16:17] op_sel:[0,1,0]
	v_pk_fma_f32 v[134:135], v[32:33], v[118:119], v[134:135] op_sel_hi:[1,0,1]
	v_pk_fma_f32 v[16:17], v[32:33], v[14:15], v[16:17] op_sel_hi:[1,0,1]
	v_pk_fma_f32 v[134:135], v[90:91], v[118:119], v[134:135] op_sel:[0,1,0]
	v_pk_fma_f32 v[16:17], v[90:91], v[14:15], v[16:17] op_sel:[0,1,0]
	v_cvt_pk_f16_f32 v118, v16, v17
	v_add_f32_dpp v134, v134, v134 quad_perm:[1,0,3,2] row_mask:0xf bank_mask:0xf bound_ctrl:1
	v_add_f32_dpp v135, v135, v135 quad_perm:[1,0,3,2] row_mask:0xf bank_mask:0xf bound_ctrl:1
	ds_read_b128 v[24:27], v94 offset:13824
	ds_read_b128 v[16:19], v94 offset:17920
	ds_read_b128 v[20:23], v94 offset:9728
	ds_read_b128 v[12:15], v94 offset:1536
	v_pk_fma_f32 v[28:29], v[124:125], v[96:97], v[28:29] op_sel_hi:[0,1,1]
	v_add_f32_dpp v134, v134, v134 quad_perm:[2,3,0,1] row_mask:0xf bank_mask:0xf bound_ctrl:1
	v_add_f32_dpp v135, v135, v135 quad_perm:[2,3,0,1] row_mask:0xf bank_mask:0xf bound_ctrl:1
	v_pk_fma_f32 v[34:35], v[124:125], v[96:97], v[34:35] op_sel:[1,0,0]
	v_add_f32_dpp v134, v134, v134 row_half_mirror row_mask:0xf bank_mask:0xf bound_ctrl:1
	v_add_f32_dpp v135, v135, v135 row_half_mirror row_mask:0xf bank_mask:0xf bound_ctrl:1
	v_pk_fma_f32 v[32:33], v[126:127], v[96:97], v[32:33] op_sel_hi:[0,1,1]
	v_pk_fma_f32 v[90:91], v[126:127], v[96:97], v[90:91] op_sel:[1,0,0]
	v_add_f32_dpp v134, v134, v134 row_mirror row_mask:0xf bank_mask:0xf bound_ctrl:1
	v_add_f32_dpp v135, v135, v135 row_mirror row_mask:0xf bank_mask:0xf bound_ctrl:1
	v_pk_fma_f32 v[28:29], v[120:121], v[134:135], v[28:29] op_sel_hi:[0,1,1]
	v_pk_fma_f32 v[34:35], v[120:121], v[134:135], v[34:35] op_sel:[1,0,0]
	v_pk_fma_f32 v[32:33], v[122:123], v[134:135], v[32:33] op_sel_hi:[0,1,1]
	v_pk_fma_f32 v[90:91], v[122:123], v[134:135], v[90:91] op_sel:[1,0,0]
	s_waitcnt lgkmcnt(0)
	v_pk_mul_f32 v[134:135], v[28:29], v[24:25] op_sel_hi:[1,0]
	v_pk_mul_f32 v[116:117], v[28:29], v[130:131] op_sel_hi:[1,0]
	v_pk_fma_f32 v[134:135], v[34:35], v[24:25], v[134:135] op_sel:[0,1,0]
	v_pk_fma_f32 v[116:117], v[34:35], v[130:131], v[116:117] op_sel:[0,1,0]
	v_pk_fma_f32 v[134:135], v[32:33], v[26:27], v[134:135] op_sel_hi:[1,0,1]
	v_pk_fma_f32 v[116:117], v[32:33], v[132:133], v[116:117] op_sel_hi:[1,0,1]
	v_pk_fma_f32 v[134:135], v[90:91], v[26:27], v[134:135] op_sel:[0,1,0]
	v_pk_fma_f32 v[116:117], v[90:91], v[132:133], v[116:117] op_sel:[0,1,0]
	v_cvt_pk_f16_f32 v116, v116, v117
	v_add_f32_dpp v134, v134, v134 quad_perm:[1,0,3,2] row_mask:0xf bank_mask:0xf bound_ctrl:1
	v_add_f32_dpp v135, v135, v135 quad_perm:[1,0,3,2] row_mask:0xf bank_mask:0xf bound_ctrl:1
	ds_write2st64_b32 v42, v118, v116 offset0:16 offset1:20
	ds_read_b128 v[116:119], v93 offset:13824
	ds_read_b128 v[120:123], v93 offset:17920
	ds_read_b128 v[124:127], v93 offset:9728
	ds_read_b128 v[130:133], v93 offset:1536
	ds_read_b64 v[96:97], v92 offset:768
	v_pk_fma_f32 v[28:29], v[20:21], v[30:31], v[28:29] op_sel_hi:[0,1,1]
	v_add_f32_dpp v134, v134, v134 quad_perm:[2,3,0,1] row_mask:0xf bank_mask:0xf bound_ctrl:1
	v_add_f32_dpp v135, v135, v135 quad_perm:[2,3,0,1] row_mask:0xf bank_mask:0xf bound_ctrl:1
	v_pk_fma_f32 v[34:35], v[20:21], v[30:31], v[34:35] op_sel:[1,0,0]
	v_add_f32_dpp v134, v134, v134 row_half_mirror row_mask:0xf bank_mask:0xf bound_ctrl:1
	v_add_f32_dpp v135, v135, v135 row_half_mirror row_mask:0xf bank_mask:0xf bound_ctrl:1
	v_pk_fma_f32 v[32:33], v[22:23], v[30:31], v[32:33] op_sel_hi:[0,1,1]
	v_pk_fma_f32 v[90:91], v[22:23], v[30:31], v[90:91] op_sel:[1,0,0]
	ds_read_b64 v[30:31], v95 offset:21504
	v_add_f32_dpp v134, v134, v134 row_mirror row_mask:0xf bank_mask:0xf bound_ctrl:1
	v_add_f32_dpp v135, v135, v135 row_mirror row_mask:0xf bank_mask:0xf bound_ctrl:1
	v_pk_fma_f32 v[28:29], v[16:17], v[134:135], v[28:29] op_sel_hi:[0,1,1]
	v_pk_fma_f32 v[34:35], v[16:17], v[134:135], v[34:35] op_sel:[1,0,0]
	v_pk_fma_f32 v[32:33], v[18:19], v[134:135], v[32:33] op_sel_hi:[0,1,1]
	v_pk_fma_f32 v[90:91], v[18:19], v[134:135], v[90:91] op_sel:[1,0,0]
	s_waitcnt lgkmcnt(1)
	v_pk_mul_f32 v[134:135], v[28:29], v[116:117] op_sel_hi:[1,0]
	v_pk_mul_f32 v[16:17], v[28:29], v[12:13] op_sel_hi:[1,0]
	v_pk_fma_f32 v[134:135], v[34:35], v[116:117], v[134:135] op_sel:[0,1,0]
	v_pk_fma_f32 v[16:17], v[34:35], v[12:13], v[16:17] op_sel:[0,1,0]
	v_pk_fma_f32 v[134:135], v[32:33], v[118:119], v[134:135] op_sel_hi:[1,0,1]
	v_pk_fma_f32 v[16:17], v[32:33], v[14:15], v[16:17] op_sel_hi:[1,0,1]
	v_pk_fma_f32 v[134:135], v[90:91], v[118:119], v[134:135] op_sel:[0,1,0]
	v_pk_fma_f32 v[16:17], v[90:91], v[14:15], v[16:17] op_sel:[0,1,0]
	v_cvt_pk_f16_f32 v118, v16, v17
	v_add_f32_dpp v134, v134, v134 quad_perm:[1,0,3,2] row_mask:0xf bank_mask:0xf bound_ctrl:1
	v_add_f32_dpp v135, v135, v135 quad_perm:[1,0,3,2] row_mask:0xf bank_mask:0xf bound_ctrl:1
	ds_read_b128 v[24:27], v94 offset:14336
	ds_read_b128 v[16:19], v94 offset:18432
	ds_read_b128 v[20:23], v94 offset:10240
	ds_read_b128 v[12:15], v94 offset:2048
	v_pk_fma_f32 v[28:29], v[124:125], v[96:97], v[28:29] op_sel_hi:[0,1,1]
	v_add_f32_dpp v134, v134, v134 quad_perm:[2,3,0,1] row_mask:0xf bank_mask:0xf bound_ctrl:1
	v_add_f32_dpp v135, v135, v135 quad_perm:[2,3,0,1] row_mask:0xf bank_mask:0xf bound_ctrl:1
	v_pk_fma_f32 v[34:35], v[124:125], v[96:97], v[34:35] op_sel:[1,0,0]
	v_add_f32_dpp v134, v134, v134 row_half_mirror row_mask:0xf bank_mask:0xf bound_ctrl:1
	v_add_f32_dpp v135, v135, v135 row_half_mirror row_mask:0xf bank_mask:0xf bound_ctrl:1
	v_pk_fma_f32 v[32:33], v[126:127], v[96:97], v[32:33] op_sel_hi:[0,1,1]
	v_pk_fma_f32 v[90:91], v[126:127], v[96:97], v[90:91] op_sel:[1,0,0]
	v_add_f32_dpp v134, v134, v134 row_mirror row_mask:0xf bank_mask:0xf bound_ctrl:1
	v_add_f32_dpp v135, v135, v135 row_mirror row_mask:0xf bank_mask:0xf bound_ctrl:1
	v_pk_fma_f32 v[28:29], v[120:121], v[134:135], v[28:29] op_sel_hi:[0,1,1]
	v_pk_fma_f32 v[34:35], v[120:121], v[134:135], v[34:35] op_sel:[1,0,0]
	v_pk_fma_f32 v[32:33], v[122:123], v[134:135], v[32:33] op_sel_hi:[0,1,1]
	v_pk_fma_f32 v[90:91], v[122:123], v[134:135], v[90:91] op_sel:[1,0,0]
	s_waitcnt lgkmcnt(0)
	v_pk_mul_f32 v[134:135], v[28:29], v[24:25] op_sel_hi:[1,0]
	v_pk_mul_f32 v[116:117], v[28:29], v[130:131] op_sel_hi:[1,0]
	v_pk_fma_f32 v[134:135], v[34:35], v[24:25], v[134:135] op_sel:[0,1,0]
	v_pk_fma_f32 v[116:117], v[34:35], v[130:131], v[116:117] op_sel:[0,1,0]
	v_pk_fma_f32 v[134:135], v[32:33], v[26:27], v[134:135] op_sel_hi:[1,0,1]
	v_pk_fma_f32 v[116:117], v[32:33], v[132:133], v[116:117] op_sel_hi:[1,0,1]
	v_pk_fma_f32 v[134:135], v[90:91], v[26:27], v[134:135] op_sel:[0,1,0]
	v_pk_fma_f32 v[116:117], v[90:91], v[132:133], v[116:117] op_sel:[0,1,0]
	v_cvt_pk_f16_f32 v116, v116, v117
	v_add_f32_dpp v134, v134, v134 quad_perm:[1,0,3,2] row_mask:0xf bank_mask:0xf bound_ctrl:1
	v_add_f32_dpp v135, v135, v135 quad_perm:[1,0,3,2] row_mask:0xf bank_mask:0xf bound_ctrl:1
	ds_write2st64_b32 v42, v118, v116 offset0:24 offset1:28
	ds_read_b128 v[116:119], v93 offset:14336
	ds_read_b128 v[120:123], v93 offset:18432
	ds_read_b128 v[124:127], v93 offset:10240
	ds_read_b128 v[130:133], v93 offset:2048
	ds_read_b64 v[96:97], v92 offset:1024
	v_pk_fma_f32 v[28:29], v[20:21], v[30:31], v[28:29] op_sel_hi:[0,1,1]
	v_add_f32_dpp v134, v134, v134 quad_perm:[2,3,0,1] row_mask:0xf bank_mask:0xf bound_ctrl:1
	v_add_f32_dpp v135, v135, v135 quad_perm:[2,3,0,1] row_mask:0xf bank_mask:0xf bound_ctrl:1
	v_pk_fma_f32 v[34:35], v[20:21], v[30:31], v[34:35] op_sel:[1,0,0]
	v_add_f32_dpp v134, v134, v134 row_half_mirror row_mask:0xf bank_mask:0xf bound_ctrl:1
	v_add_f32_dpp v135, v135, v135 row_half_mirror row_mask:0xf bank_mask:0xf bound_ctrl:1
	v_pk_fma_f32 v[32:33], v[22:23], v[30:31], v[32:33] op_sel_hi:[0,1,1]
	v_pk_fma_f32 v[90:91], v[22:23], v[30:31], v[90:91] op_sel:[1,0,0]
	ds_read_b64 v[30:31], v95 offset:21760
	v_add_f32_dpp v134, v134, v134 row_mirror row_mask:0xf bank_mask:0xf bound_ctrl:1
	v_add_f32_dpp v135, v135, v135 row_mirror row_mask:0xf bank_mask:0xf bound_ctrl:1
	v_pk_fma_f32 v[28:29], v[16:17], v[134:135], v[28:29] op_sel_hi:[0,1,1]
	v_pk_fma_f32 v[34:35], v[16:17], v[134:135], v[34:35] op_sel:[1,0,0]
	v_pk_fma_f32 v[32:33], v[18:19], v[134:135], v[32:33] op_sel_hi:[0,1,1]
	v_pk_fma_f32 v[90:91], v[18:19], v[134:135], v[90:91] op_sel:[1,0,0]
	s_waitcnt lgkmcnt(1)
	v_pk_mul_f32 v[134:135], v[28:29], v[116:117] op_sel_hi:[1,0]
	v_pk_mul_f32 v[16:17], v[28:29], v[12:13] op_sel_hi:[1,0]
	v_pk_fma_f32 v[134:135], v[34:35], v[116:117], v[134:135] op_sel:[0,1,0]
	v_pk_fma_f32 v[16:17], v[34:35], v[12:13], v[16:17] op_sel:[0,1,0]
	v_pk_fma_f32 v[134:135], v[32:33], v[118:119], v[134:135] op_sel_hi:[1,0,1]
	v_pk_fma_f32 v[16:17], v[32:33], v[14:15], v[16:17] op_sel_hi:[1,0,1]
	v_pk_fma_f32 v[134:135], v[90:91], v[118:119], v[134:135] op_sel:[0,1,0]
	v_pk_fma_f32 v[16:17], v[90:91], v[14:15], v[16:17] op_sel:[0,1,0]
	v_cvt_pk_f16_f32 v118, v16, v17
	v_add_f32_dpp v134, v134, v134 quad_perm:[1,0,3,2] row_mask:0xf bank_mask:0xf bound_ctrl:1
	v_add_f32_dpp v135, v135, v135 quad_perm:[1,0,3,2] row_mask:0xf bank_mask:0xf bound_ctrl:1
	ds_read_b128 v[24:27], v94 offset:14848
	ds_read_b128 v[16:19], v94 offset:18944
	ds_read_b128 v[20:23], v94 offset:10752
	ds_read_b128 v[12:15], v94 offset:2560
	v_pk_fma_f32 v[28:29], v[124:125], v[96:97], v[28:29] op_sel_hi:[0,1,1]
	v_add_f32_dpp v134, v134, v134 quad_perm:[2,3,0,1] row_mask:0xf bank_mask:0xf bound_ctrl:1
	v_add_f32_dpp v135, v135, v135 quad_perm:[2,3,0,1] row_mask:0xf bank_mask:0xf bound_ctrl:1
	v_pk_fma_f32 v[34:35], v[124:125], v[96:97], v[34:35] op_sel:[1,0,0]
	v_add_f32_dpp v134, v134, v134 row_half_mirror row_mask:0xf bank_mask:0xf bound_ctrl:1
	v_add_f32_dpp v135, v135, v135 row_half_mirror row_mask:0xf bank_mask:0xf bound_ctrl:1
	v_pk_fma_f32 v[32:33], v[126:127], v[96:97], v[32:33] op_sel_hi:[0,1,1]
	v_pk_fma_f32 v[90:91], v[126:127], v[96:97], v[90:91] op_sel:[1,0,0]
	v_add_f32_dpp v134, v134, v134 row_mirror row_mask:0xf bank_mask:0xf bound_ctrl:1
	v_add_f32_dpp v135, v135, v135 row_mirror row_mask:0xf bank_mask:0xf bound_ctrl:1
	v_pk_fma_f32 v[28:29], v[120:121], v[134:135], v[28:29] op_sel_hi:[0,1,1]
	v_pk_fma_f32 v[34:35], v[120:121], v[134:135], v[34:35] op_sel:[1,0,0]
	v_pk_fma_f32 v[32:33], v[122:123], v[134:135], v[32:33] op_sel_hi:[0,1,1]
	v_pk_fma_f32 v[90:91], v[122:123], v[134:135], v[90:91] op_sel:[1,0,0]
	s_waitcnt lgkmcnt(0)
	v_pk_mul_f32 v[134:135], v[28:29], v[24:25] op_sel_hi:[1,0]
	v_pk_mul_f32 v[116:117], v[28:29], v[130:131] op_sel_hi:[1,0]
	v_pk_fma_f32 v[134:135], v[34:35], v[24:25], v[134:135] op_sel:[0,1,0]
	v_pk_fma_f32 v[116:117], v[34:35], v[130:131], v[116:117] op_sel:[0,1,0]
	v_pk_fma_f32 v[134:135], v[32:33], v[26:27], v[134:135] op_sel_hi:[1,0,1]
	v_pk_fma_f32 v[116:117], v[32:33], v[132:133], v[116:117] op_sel_hi:[1,0,1]
	v_pk_fma_f32 v[134:135], v[90:91], v[26:27], v[134:135] op_sel:[0,1,0]
	v_pk_fma_f32 v[116:117], v[90:91], v[132:133], v[116:117] op_sel:[0,1,0]
	v_cvt_pk_f16_f32 v116, v116, v117
	v_add_f32_dpp v134, v134, v134 quad_perm:[1,0,3,2] row_mask:0xf bank_mask:0xf bound_ctrl:1
	v_add_f32_dpp v135, v135, v135 quad_perm:[1,0,3,2] row_mask:0xf bank_mask:0xf bound_ctrl:1
	ds_write2st64_b32 v42, v118, v116 offset0:32 offset1:36
	ds_read_b128 v[116:119], v93 offset:14848
	ds_read_b128 v[120:123], v93 offset:18944
	ds_read_b128 v[124:127], v93 offset:10752
	ds_read_b128 v[130:133], v93 offset:2560
	ds_read_b64 v[96:97], v92 offset:1280
	v_pk_fma_f32 v[28:29], v[20:21], v[30:31], v[28:29] op_sel_hi:[0,1,1]
	v_add_f32_dpp v134, v134, v134 quad_perm:[2,3,0,1] row_mask:0xf bank_mask:0xf bound_ctrl:1
	v_add_f32_dpp v135, v135, v135 quad_perm:[2,3,0,1] row_mask:0xf bank_mask:0xf bound_ctrl:1
	v_pk_fma_f32 v[34:35], v[20:21], v[30:31], v[34:35] op_sel:[1,0,0]
	v_add_f32_dpp v134, v134, v134 row_half_mirror row_mask:0xf bank_mask:0xf bound_ctrl:1
	v_add_f32_dpp v135, v135, v135 row_half_mirror row_mask:0xf bank_mask:0xf bound_ctrl:1
	v_pk_fma_f32 v[32:33], v[22:23], v[30:31], v[32:33] op_sel_hi:[0,1,1]
	v_pk_fma_f32 v[90:91], v[22:23], v[30:31], v[90:91] op_sel:[1,0,0]
	ds_read_b64 v[30:31], v95 offset:22016
	v_add_f32_dpp v134, v134, v134 row_mirror row_mask:0xf bank_mask:0xf bound_ctrl:1
	v_add_f32_dpp v135, v135, v135 row_mirror row_mask:0xf bank_mask:0xf bound_ctrl:1
	v_pk_fma_f32 v[28:29], v[16:17], v[134:135], v[28:29] op_sel_hi:[0,1,1]
	v_pk_fma_f32 v[34:35], v[16:17], v[134:135], v[34:35] op_sel:[1,0,0]
	v_pk_fma_f32 v[32:33], v[18:19], v[134:135], v[32:33] op_sel_hi:[0,1,1]
	v_pk_fma_f32 v[90:91], v[18:19], v[134:135], v[90:91] op_sel:[1,0,0]
	s_waitcnt lgkmcnt(1)
	v_pk_mul_f32 v[134:135], v[28:29], v[116:117] op_sel_hi:[1,0]
	v_pk_mul_f32 v[16:17], v[28:29], v[12:13] op_sel_hi:[1,0]
	v_pk_fma_f32 v[134:135], v[34:35], v[116:117], v[134:135] op_sel:[0,1,0]
	v_pk_fma_f32 v[16:17], v[34:35], v[12:13], v[16:17] op_sel:[0,1,0]
	v_pk_fma_f32 v[134:135], v[32:33], v[118:119], v[134:135] op_sel_hi:[1,0,1]
	v_pk_fma_f32 v[16:17], v[32:33], v[14:15], v[16:17] op_sel_hi:[1,0,1]
	v_pk_fma_f32 v[134:135], v[90:91], v[118:119], v[134:135] op_sel:[0,1,0]
	v_pk_fma_f32 v[16:17], v[90:91], v[14:15], v[16:17] op_sel:[0,1,0]
	v_cvt_pk_f16_f32 v118, v16, v17
	v_add_f32_dpp v134, v134, v134 quad_perm:[1,0,3,2] row_mask:0xf bank_mask:0xf bound_ctrl:1
	v_add_f32_dpp v135, v135, v135 quad_perm:[1,0,3,2] row_mask:0xf bank_mask:0xf bound_ctrl:1
	ds_read_b128 v[24:27], v94 offset:15360
	ds_read_b128 v[16:19], v94 offset:19456
	ds_read_b128 v[20:23], v94 offset:11264
	ds_read_b128 v[12:15], v94 offset:3072
	v_pk_fma_f32 v[28:29], v[124:125], v[96:97], v[28:29] op_sel_hi:[0,1,1]
	v_add_f32_dpp v134, v134, v134 quad_perm:[2,3,0,1] row_mask:0xf bank_mask:0xf bound_ctrl:1
	v_add_f32_dpp v135, v135, v135 quad_perm:[2,3,0,1] row_mask:0xf bank_mask:0xf bound_ctrl:1
	v_pk_fma_f32 v[34:35], v[124:125], v[96:97], v[34:35] op_sel:[1,0,0]
	v_add_f32_dpp v134, v134, v134 row_half_mirror row_mask:0xf bank_mask:0xf bound_ctrl:1
	v_add_f32_dpp v135, v135, v135 row_half_mirror row_mask:0xf bank_mask:0xf bound_ctrl:1
	v_pk_fma_f32 v[32:33], v[126:127], v[96:97], v[32:33] op_sel_hi:[0,1,1]
	v_pk_fma_f32 v[90:91], v[126:127], v[96:97], v[90:91] op_sel:[1,0,0]
	v_add_f32_dpp v134, v134, v134 row_mirror row_mask:0xf bank_mask:0xf bound_ctrl:1
	v_add_f32_dpp v135, v135, v135 row_mirror row_mask:0xf bank_mask:0xf bound_ctrl:1
	v_pk_fma_f32 v[28:29], v[120:121], v[134:135], v[28:29] op_sel_hi:[0,1,1]
	v_pk_fma_f32 v[34:35], v[120:121], v[134:135], v[34:35] op_sel:[1,0,0]
	v_pk_fma_f32 v[32:33], v[122:123], v[134:135], v[32:33] op_sel_hi:[0,1,1]
	v_pk_fma_f32 v[90:91], v[122:123], v[134:135], v[90:91] op_sel:[1,0,0]
	s_waitcnt lgkmcnt(0)
	v_pk_mul_f32 v[134:135], v[28:29], v[24:25] op_sel_hi:[1,0]
	v_pk_mul_f32 v[116:117], v[28:29], v[130:131] op_sel_hi:[1,0]
	v_pk_fma_f32 v[134:135], v[34:35], v[24:25], v[134:135] op_sel:[0,1,0]
	v_pk_fma_f32 v[116:117], v[34:35], v[130:131], v[116:117] op_sel:[0,1,0]
	v_pk_fma_f32 v[134:135], v[32:33], v[26:27], v[134:135] op_sel_hi:[1,0,1]
	v_pk_fma_f32 v[116:117], v[32:33], v[132:133], v[116:117] op_sel_hi:[1,0,1]
	v_pk_fma_f32 v[134:135], v[90:91], v[26:27], v[134:135] op_sel:[0,1,0]
	v_pk_fma_f32 v[116:117], v[90:91], v[132:133], v[116:117] op_sel:[0,1,0]
	v_cvt_pk_f16_f32 v116, v116, v117
	v_add_f32_dpp v134, v134, v134 quad_perm:[1,0,3,2] row_mask:0xf bank_mask:0xf bound_ctrl:1
	v_add_f32_dpp v135, v135, v135 quad_perm:[1,0,3,2] row_mask:0xf bank_mask:0xf bound_ctrl:1
	ds_write2st64_b32 v42, v118, v116 offset0:40 offset1:44
	ds_read_b128 v[116:119], v93 offset:15360
	ds_read_b128 v[120:123], v93 offset:19456
	ds_read_b128 v[124:127], v93 offset:11264
	ds_read_b128 v[130:133], v93 offset:3072
	ds_read_b64 v[96:97], v92 offset:1536
	v_pk_fma_f32 v[28:29], v[20:21], v[30:31], v[28:29] op_sel_hi:[0,1,1]
	v_add_f32_dpp v134, v134, v134 quad_perm:[2,3,0,1] row_mask:0xf bank_mask:0xf bound_ctrl:1
	v_add_f32_dpp v135, v135, v135 quad_perm:[2,3,0,1] row_mask:0xf bank_mask:0xf bound_ctrl:1
	v_pk_fma_f32 v[34:35], v[20:21], v[30:31], v[34:35] op_sel:[1,0,0]
	v_add_f32_dpp v134, v134, v134 row_half_mirror row_mask:0xf bank_mask:0xf bound_ctrl:1
	v_add_f32_dpp v135, v135, v135 row_half_mirror row_mask:0xf bank_mask:0xf bound_ctrl:1
	v_pk_fma_f32 v[32:33], v[22:23], v[30:31], v[32:33] op_sel_hi:[0,1,1]
	v_pk_fma_f32 v[90:91], v[22:23], v[30:31], v[90:91] op_sel:[1,0,0]
	ds_read_b64 v[30:31], v95 offset:22272
	v_add_f32_dpp v134, v134, v134 row_mirror row_mask:0xf bank_mask:0xf bound_ctrl:1
	v_add_f32_dpp v135, v135, v135 row_mirror row_mask:0xf bank_mask:0xf bound_ctrl:1
	v_pk_fma_f32 v[28:29], v[16:17], v[134:135], v[28:29] op_sel_hi:[0,1,1]
	v_pk_fma_f32 v[34:35], v[16:17], v[134:135], v[34:35] op_sel:[1,0,0]
	v_pk_fma_f32 v[32:33], v[18:19], v[134:135], v[32:33] op_sel_hi:[0,1,1]
	v_pk_fma_f32 v[90:91], v[18:19], v[134:135], v[90:91] op_sel:[1,0,0]
	s_waitcnt lgkmcnt(1)
	v_pk_mul_f32 v[134:135], v[28:29], v[116:117] op_sel_hi:[1,0]
	v_pk_mul_f32 v[16:17], v[28:29], v[12:13] op_sel_hi:[1,0]
	v_pk_fma_f32 v[134:135], v[34:35], v[116:117], v[134:135] op_sel:[0,1,0]
	v_pk_fma_f32 v[16:17], v[34:35], v[12:13], v[16:17] op_sel:[0,1,0]
	v_pk_fma_f32 v[134:135], v[32:33], v[118:119], v[134:135] op_sel_hi:[1,0,1]
	v_pk_fma_f32 v[16:17], v[32:33], v[14:15], v[16:17] op_sel_hi:[1,0,1]
	v_pk_fma_f32 v[134:135], v[90:91], v[118:119], v[134:135] op_sel:[0,1,0]
	v_pk_fma_f32 v[16:17], v[90:91], v[14:15], v[16:17] op_sel:[0,1,0]
	v_cvt_pk_f16_f32 v118, v16, v17
	v_add_f32_dpp v134, v134, v134 quad_perm:[1,0,3,2] row_mask:0xf bank_mask:0xf bound_ctrl:1
	v_add_f32_dpp v135, v135, v135 quad_perm:[1,0,3,2] row_mask:0xf bank_mask:0xf bound_ctrl:1
	ds_read_b128 v[24:27], v94 offset:15872
	ds_read_b128 v[16:19], v94 offset:19968
	ds_read_b128 v[20:23], v94 offset:11776
	ds_read_b128 v[12:15], v94 offset:3584
	v_pk_fma_f32 v[28:29], v[124:125], v[96:97], v[28:29] op_sel_hi:[0,1,1]
	v_add_f32_dpp v134, v134, v134 quad_perm:[2,3,0,1] row_mask:0xf bank_mask:0xf bound_ctrl:1
	v_add_f32_dpp v135, v135, v135 quad_perm:[2,3,0,1] row_mask:0xf bank_mask:0xf bound_ctrl:1
	v_pk_fma_f32 v[34:35], v[124:125], v[96:97], v[34:35] op_sel:[1,0,0]
	v_add_f32_dpp v134, v134, v134 row_half_mirror row_mask:0xf bank_mask:0xf bound_ctrl:1
	v_add_f32_dpp v135, v135, v135 row_half_mirror row_mask:0xf bank_mask:0xf bound_ctrl:1
	v_pk_fma_f32 v[32:33], v[126:127], v[96:97], v[32:33] op_sel_hi:[0,1,1]
	v_pk_fma_f32 v[90:91], v[126:127], v[96:97], v[90:91] op_sel:[1,0,0]
	v_add_f32_dpp v134, v134, v134 row_mirror row_mask:0xf bank_mask:0xf bound_ctrl:1
	v_add_f32_dpp v135, v135, v135 row_mirror row_mask:0xf bank_mask:0xf bound_ctrl:1
	v_pk_fma_f32 v[28:29], v[120:121], v[134:135], v[28:29] op_sel_hi:[0,1,1]
	v_pk_fma_f32 v[34:35], v[120:121], v[134:135], v[34:35] op_sel:[1,0,0]
	v_pk_fma_f32 v[32:33], v[122:123], v[134:135], v[32:33] op_sel_hi:[0,1,1]
	v_pk_fma_f32 v[90:91], v[122:123], v[134:135], v[90:91] op_sel:[1,0,0]
	s_waitcnt lgkmcnt(0)
	v_pk_mul_f32 v[134:135], v[28:29], v[24:25] op_sel_hi:[1,0]
	v_pk_mul_f32 v[116:117], v[28:29], v[130:131] op_sel_hi:[1,0]
	v_pk_fma_f32 v[134:135], v[34:35], v[24:25], v[134:135] op_sel:[0,1,0]
	v_pk_fma_f32 v[116:117], v[34:35], v[130:131], v[116:117] op_sel:[0,1,0]
	v_pk_fma_f32 v[134:135], v[32:33], v[26:27], v[134:135] op_sel_hi:[1,0,1]
	v_pk_fma_f32 v[116:117], v[32:33], v[132:133], v[116:117] op_sel_hi:[1,0,1]
	v_pk_fma_f32 v[134:135], v[90:91], v[26:27], v[134:135] op_sel:[0,1,0]
	v_pk_fma_f32 v[116:117], v[90:91], v[132:133], v[116:117] op_sel:[0,1,0]
	v_cvt_pk_f16_f32 v116, v116, v117
	v_add_f32_dpp v134, v134, v134 quad_perm:[1,0,3,2] row_mask:0xf bank_mask:0xf bound_ctrl:1
	v_add_f32_dpp v135, v135, v135 quad_perm:[1,0,3,2] row_mask:0xf bank_mask:0xf bound_ctrl:1
	ds_write2st64_b32 v42, v118, v116 offset0:48 offset1:52
	ds_read_b128 v[116:119], v93 offset:15872
	ds_read_b128 v[120:123], v93 offset:19968
	ds_read_b128 v[124:127], v93 offset:11776
	ds_read_b128 v[130:133], v93 offset:3584
	ds_read_b64 v[96:97], v92 offset:1792
	v_pk_fma_f32 v[28:29], v[20:21], v[30:31], v[28:29] op_sel_hi:[0,1,1]
	v_add_f32_dpp v134, v134, v134 quad_perm:[2,3,0,1] row_mask:0xf bank_mask:0xf bound_ctrl:1
	v_add_f32_dpp v135, v135, v135 quad_perm:[2,3,0,1] row_mask:0xf bank_mask:0xf bound_ctrl:1
	v_pk_fma_f32 v[34:35], v[20:21], v[30:31], v[34:35] op_sel:[1,0,0]
	v_add_f32_dpp v134, v134, v134 row_half_mirror row_mask:0xf bank_mask:0xf bound_ctrl:1
	v_add_f32_dpp v135, v135, v135 row_half_mirror row_mask:0xf bank_mask:0xf bound_ctrl:1
	v_pk_fma_f32 v[32:33], v[22:23], v[30:31], v[32:33] op_sel_hi:[0,1,1]
	v_pk_fma_f32 v[90:91], v[22:23], v[30:31], v[90:91] op_sel:[1,0,0]
	ds_read_b64 v[30:31], v95 offset:22272
	v_add_f32_dpp v134, v134, v134 row_mirror row_mask:0xf bank_mask:0xf bound_ctrl:1
	v_add_f32_dpp v135, v135, v135 row_mirror row_mask:0xf bank_mask:0xf bound_ctrl:1
	v_pk_fma_f32 v[28:29], v[16:17], v[134:135], v[28:29] op_sel_hi:[0,1,1]
	v_pk_fma_f32 v[34:35], v[16:17], v[134:135], v[34:35] op_sel:[1,0,0]
	v_pk_fma_f32 v[32:33], v[18:19], v[134:135], v[32:33] op_sel_hi:[0,1,1]
	v_pk_fma_f32 v[90:91], v[18:19], v[134:135], v[90:91] op_sel:[1,0,0]
	s_waitcnt lgkmcnt(1)
	v_pk_mul_f32 v[134:135], v[28:29], v[116:117] op_sel_hi:[1,0]
	v_pk_mul_f32 v[16:17], v[28:29], v[12:13] op_sel_hi:[1,0]
	v_pk_fma_f32 v[134:135], v[34:35], v[116:117], v[134:135] op_sel:[0,1,0]
	v_pk_fma_f32 v[16:17], v[34:35], v[12:13], v[16:17] op_sel:[0,1,0]
	v_pk_fma_f32 v[134:135], v[32:33], v[118:119], v[134:135] op_sel_hi:[1,0,1]
	v_pk_fma_f32 v[16:17], v[32:33], v[14:15], v[16:17] op_sel_hi:[1,0,1]
	v_pk_fma_f32 v[134:135], v[90:91], v[118:119], v[134:135] op_sel:[0,1,0]
	v_pk_fma_f32 v[16:17], v[90:91], v[14:15], v[16:17] op_sel:[0,1,0]
	v_cvt_pk_f16_f32 v118, v16, v17
	v_add_f32_dpp v134, v134, v134 quad_perm:[1,0,3,2] row_mask:0xf bank_mask:0xf bound_ctrl:1
	v_add_f32_dpp v135, v135, v135 quad_perm:[1,0,3,2] row_mask:0xf bank_mask:0xf bound_ctrl:1
	ds_read_b128 v[24:27], v94 offset:15872
	ds_read_b128 v[16:19], v94 offset:19968
	ds_read_b128 v[20:23], v94 offset:11776
	ds_read_b128 v[12:15], v94 offset:3584
	v_pk_fma_f32 v[28:29], v[124:125], v[96:97], v[28:29] op_sel_hi:[0,1,1]
	v_add_f32_dpp v134, v134, v134 quad_perm:[2,3,0,1] row_mask:0xf bank_mask:0xf bound_ctrl:1
	v_add_f32_dpp v135, v135, v135 quad_perm:[2,3,0,1] row_mask:0xf bank_mask:0xf bound_ctrl:1
	v_pk_fma_f32 v[34:35], v[124:125], v[96:97], v[34:35] op_sel:[1,0,0]
	v_add_f32_dpp v134, v134, v134 row_half_mirror row_mask:0xf bank_mask:0xf bound_ctrl:1
	v_add_f32_dpp v135, v135, v135 row_half_mirror row_mask:0xf bank_mask:0xf bound_ctrl:1
	v_pk_fma_f32 v[32:33], v[126:127], v[96:97], v[32:33] op_sel_hi:[0,1,1]
	v_pk_fma_f32 v[90:91], v[126:127], v[96:97], v[90:91] op_sel:[1,0,0]
	v_add_f32_dpp v134, v134, v134 row_mirror row_mask:0xf bank_mask:0xf bound_ctrl:1
	v_add_f32_dpp v135, v135, v135 row_mirror row_mask:0xf bank_mask:0xf bound_ctrl:1
	v_pk_fma_f32 v[28:29], v[120:121], v[134:135], v[28:29] op_sel_hi:[0,1,1]
	v_pk_fma_f32 v[34:35], v[120:121], v[134:135], v[34:35] op_sel:[1,0,0]
	v_pk_fma_f32 v[32:33], v[122:123], v[134:135], v[32:33] op_sel_hi:[0,1,1]
	v_pk_fma_f32 v[90:91], v[122:123], v[134:135], v[90:91] op_sel:[1,0,0]
	v_pk_mul_f32 v[116:117], v[28:29], v[130:131] op_sel_hi:[1,0]
	v_pk_fma_f32 v[116:117], v[34:35], v[130:131], v[116:117] op_sel:[0,1,0]
	v_pk_fma_f32 v[116:117], v[32:33], v[132:133], v[116:117] op_sel_hi:[1,0,1]
	v_pk_fma_f32 v[116:117], v[90:91], v[132:133], v[116:117] op_sel:[0,1,0]
	v_cvt_pk_f16_f32 v116, v116, v117
	ds_write2st64_b32 v42, v118, v116 offset0:56 offset1:60
	s_waitcnt vmcnt(4) lgkmcnt(1)
	v_cvt_f32_f16_sdwa v31, v72 dst_sel:DWORD dst_unused:UNUSED_PAD src0_sel:WORD_1
	v_cvt_f32_f16_e32 v30, v72
	v_cvt_f32_f16_sdwa v93, v73 dst_sel:DWORD dst_unused:UNUSED_PAD src0_sel:WORD_1
	v_cvt_f32_f16_e32 v92, v73
	s_waitcnt vmcnt(1)
	v_cvt_f32_f16_sdwa v17, v80 dst_sel:DWORD dst_unused:UNUSED_PAD src0_sel:WORD_1
	v_cvt_f32_f16_e32 v16, v80
	v_cvt_f32_f16_sdwa v19, v81 dst_sel:DWORD dst_unused:UNUSED_PAD src0_sel:WORD_1
	v_cvt_f32_f16_e32 v18, v81
	v_pk_mul_f32 v[22:23], v[0:1], v[30:31]
	v_pk_mul_f32 v[20:21], v[2:3], v[92:93]
	v_pk_mul_f32 v[96:97], v[22:23], v[22:23]
	ds_read_b128 v[12:15], v94 offset:7936
	v_pk_mul_f32 v[94:95], v[20:21], v[20:21]
	v_add_f32_e32 v42, v96, v97
	v_cvt_f32_f16_sdwa v25, v70 dst_sel:DWORD dst_unused:UNUSED_PAD src0_sel:WORD_1
	v_cvt_f32_f16_e32 v24, v70
	v_cvt_f32_f16_sdwa v27, v71 dst_sel:DWORD dst_unused:UNUSED_PAD src0_sel:WORD_1
	v_cvt_f32_f16_e32 v26, v71
	v_add_f32_e32 v42, v94, v42
	v_add_f32_e32 v42, v95, v42
	v_pk_add_f32 v[94:95], v[16:17], -1.0 op_sel_hi:[1,0]
	v_pk_add_f32 v[96:97], v[18:19], -1.0 op_sel_hi:[1,0]
	v_pk_fma_f32 v[94:95], v[4:5], v[94:95], 1.0 op_sel_hi:[1,1,0]
	v_pk_fma_f32 v[96:97], v[6:7], v[96:97], 1.0 op_sel_hi:[1,1,0]
	v_pk_mul_f32 v[94:95], v[30:31], v[94:95]
	v_pk_mul_f32 v[96:97], v[92:93], v[96:97]
	v_pk_mul_f32 v[30:31], v[24:25], v[94:95]
	v_pk_mul_f32 v[92:93], v[26:27], v[96:97]
	v_pk_mul_f32 v[30:31], v[8:9], v[30:31]
	v_pk_mul_f32 v[92:93], v[10:11], v[92:93]
	v_add_f32_e32 v30, v30, v31
	v_add_f32_e32 v31, v92, v93
	v_add_f32_e32 v30, v30, v31
	v_add_f32_dpp v42, v42, v42 quad_perm:[1,0,3,2] row_mask:0xf bank_mask:0xf bound_ctrl:1
	s_nop 0
	v_add_f32_dpp v30, v30, v30 quad_perm:[1,0,3,2] row_mask:0xf bank_mask:0xf bound_ctrl:1
	v_add_f32_dpp v42, v42, v42 quad_perm:[2,3,0,1] row_mask:0xf bank_mask:0xf bound_ctrl:1
	s_nop 0
	v_add_f32_dpp v30, v30, v30 quad_perm:[2,3,0,1] row_mask:0xf bank_mask:0xf bound_ctrl:1
	v_add_f32_dpp v42, v42, v42 row_half_mirror row_mask:0xf bank_mask:0xf bound_ctrl:1
	s_nop 0
	v_add_f32_dpp v30, v30, v30 row_half_mirror row_mask:0xf bank_mask:0xf bound_ctrl:1
	v_mov_b32_dpp v116, v42 row_mirror row_mask:0xf bank_mask:0xf bound_ctrl:1
	s_nop 0
	v_mov_b32_dpp v31, v30 row_mirror row_mask:0xf bank_mask:0xf bound_ctrl:1
	s_and_saveexec_b64 s[12:13], s[6:7]
	s_cbranch_execz .LBB0_430
	s_add_i32 s42, s95, 16
	v_cmp_lt_u32_e32 vcc, s42, v106
	s_and_b64 exec, exec, vcc
	s_cbranch_execz .LBB0_430
	v_add_f32_e32 v92, v30, v31
	v_add_u32_e32 v30, s42, v46
	v_ashrrev_i32_e32 v31, 31, v30
	v_lshlrev_b64 v[30:31], 6, v[30:31]
	v_lshl_add_u64 v[30:31], s[58:59], 0, v[30:31]
	global_store_dword v[30:31], v92, off

.LBB0_436:
	s_or_b64 exec, exec, s[12:13]
	v_pk_mul_f32 v[92:93], v[28:29], v[12:13] op_sel_hi:[1,0]
	ds_read_b64 v[96:97], v115 offset:20480
	ds_read_b128 v[16:19], v114
	ds_read_b128 v[28:31], v114 offset:8192
	ds_read_b128 v[20:23], v114 offset:16384
	ds_read_b128 v[24:27], v114 offset:12288
	v_pk_mul_f32 v[32:33], v[32:33], v[14:15] op_sel_hi:[1,0]
	v_pk_mul_f32 v[94:95], v[34:35], v[12:13] op_sel:[0,1]
	v_pk_mul_f32 v[34:35], v[90:91], v[14:15] op_sel:[0,1]
	s_mov_b32 s12, 0
.LBB0_437:
	s_waitcnt lgkmcnt(0)
	v_pk_mul_f32 v[130:131], v[92:93], v[24:25] op_sel_hi:[1,0]
	v_pk_fma_f32 v[130:131], v[94:95], v[24:25], v[130:131] op_sel:[0,1,0]
	v_pk_fma_f32 v[130:131], v[32:33], v[26:27], v[130:131] op_sel_hi:[1,0,1]
	v_pk_fma_f32 v[130:131], v[34:35], v[26:27], v[130:131] op_sel:[0,1,0]
	ds_read_b128 v[12:15], v113 offset:12288
	ds_read_b128 v[116:119], v113 offset:16384
	ds_read_b128 v[120:123], v113 offset:8192
	ds_read_b128 v[124:127], v113
	ds_read_b64 v[90:91], v112
	v_pk_fma_f32 v[92:93], v[28:29], v[96:97], v[92:93] op_sel_hi:[0,1,1]
	v_pk_fma_f32 v[94:95], v[28:29], v[96:97], v[94:95] op_sel:[1,0,0]
	v_add_f32_dpp v130, v130, v130 quad_perm:[1,0,3,2] row_mask:0xf bank_mask:0xf bound_ctrl:1
	v_add_f32_dpp v131, v131, v131 quad_perm:[1,0,3,2] row_mask:0xf bank_mask:0xf bound_ctrl:1
	v_pk_fma_f32 v[32:33], v[30:31], v[96:97], v[32:33] op_sel_hi:[0,1,1]
	v_add_f32_dpp v130, v130, v130 quad_perm:[2,3,0,1] row_mask:0xf bank_mask:0xf bound_ctrl:1
	v_add_f32_dpp v131, v131, v131 quad_perm:[2,3,0,1] row_mask:0xf bank_mask:0xf bound_ctrl:1
	v_pk_fma_f32 v[34:35], v[30:31], v[96:97], v[34:35] op_sel:[1,0,0]
	v_add_f32_dpp v130, v130, v130 row_half_mirror row_mask:0xf bank_mask:0xf bound_ctrl:1
	v_add_f32_dpp v131, v131, v131 row_half_mirror row_mask:0xf bank_mask:0xf bound_ctrl:1
	ds_read_b64 v[96:97], v115 offset:20736
	v_add_f32_dpp v130, v130, v130 row_mirror row_mask:0xf bank_mask:0xf bound_ctrl:1
	v_add_f32_dpp v131, v131, v131 row_mirror row_mask:0xf bank_mask:0xf bound_ctrl:1
	v_pk_fma_f32 v[92:93], v[20:21], v[130:131], v[92:93] op_sel_hi:[0,1,1]
	v_pk_fma_f32 v[94:95], v[20:21], v[130:131], v[94:95] op_sel:[1,0,0]
	v_pk_fma_f32 v[32:33], v[22:23], v[130:131], v[32:33] op_sel_hi:[0,1,1]
	v_pk_fma_f32 v[34:35], v[22:23], v[130:131], v[34:35] op_sel:[1,0,0]
	s_waitcnt lgkmcnt(1)
	v_pk_mul_f32 v[130:131], v[92:93], v[12:13] op_sel_hi:[1,0]
	v_pk_mul_f32 v[20:21], v[92:93], v[16:17] op_sel_hi:[1,0]
	v_pk_fma_f32 v[130:131], v[94:95], v[12:13], v[130:131] op_sel:[0,1,0]
	v_pk_fma_f32 v[20:21], v[94:95], v[16:17], v[20:21] op_sel:[0,1,0]
	v_pk_fma_f32 v[130:131], v[32:33], v[14:15], v[130:131] op_sel_hi:[1,0,1]
	v_pk_fma_f32 v[20:21], v[32:33], v[18:19], v[20:21] op_sel_hi:[1,0,1]
	v_pk_fma_f32 v[130:131], v[34:35], v[14:15], v[130:131] op_sel:[0,1,0]
	v_pk_fma_f32 v[20:21], v[34:35], v[18:19], v[20:21] op_sel:[0,1,0]
	v_cvt_pk_f16_f32 v14, v20, v21
	v_add_f32_dpp v130, v130, v130 quad_perm:[1,0,3,2] row_mask:0xf bank_mask:0xf bound_ctrl:1
	v_add_f32_dpp v131, v131, v131 quad_perm:[1,0,3,2] row_mask:0xf bank_mask:0xf bound_ctrl:1
	ds_read_b128 v[24:27], v114 offset:12800
	ds_read_b128 v[20:23], v114 offset:16896
	ds_read_b128 v[28:31], v114 offset:8704
	ds_read_b128 v[16:19], v114 offset:512
	v_pk_fma_f32 v[92:93], v[120:121], v[90:91], v[92:93] op_sel_hi:[0,1,1]
	v_add_f32_dpp v130, v130, v130 quad_perm:[2,3,0,1] row_mask:0xf bank_mask:0xf bound_ctrl:1
	v_add_f32_dpp v131, v131, v131 quad_perm:[2,3,0,1] row_mask:0xf bank_mask:0xf bound_ctrl:1
	v_pk_fma_f32 v[94:95], v[120:121], v[90:91], v[94:95] op_sel:[1,0,0]
	v_add_f32_dpp v130, v130, v130 row_half_mirror row_mask:0xf bank_mask:0xf bound_ctrl:1
	v_add_f32_dpp v131, v131, v131 row_half_mirror row_mask:0xf bank_mask:0xf bound_ctrl:1
	v_pk_fma_f32 v[32:33], v[122:123], v[90:91], v[32:33] op_sel_hi:[0,1,1]
	v_pk_fma_f32 v[34:35], v[122:123], v[90:91], v[34:35] op_sel:[1,0,0]
	v_add_f32_dpp v130, v130, v130 row_mirror row_mask:0xf bank_mask:0xf bound_ctrl:1
	v_add_f32_dpp v131, v131, v131 row_mirror row_mask:0xf bank_mask:0xf bound_ctrl:1
	v_pk_fma_f32 v[92:93], v[116:117], v[130:131], v[92:93] op_sel_hi:[0,1,1]
	v_pk_fma_f32 v[94:95], v[116:117], v[130:131], v[94:95] op_sel:[1,0,0]
	v_pk_fma_f32 v[32:33], v[118:119], v[130:131], v[32:33] op_sel_hi:[0,1,1]
	v_pk_fma_f32 v[34:35], v[118:119], v[130:131], v[34:35] op_sel:[1,0,0]
	s_waitcnt lgkmcnt(0)
	v_pk_mul_f32 v[130:131], v[92:93], v[24:25] op_sel_hi:[1,0]
	v_pk_mul_f32 v[12:13], v[92:93], v[124:125] op_sel_hi:[1,0]
	v_pk_fma_f32 v[130:131], v[94:95], v[24:25], v[130:131] op_sel:[0,1,0]
	v_pk_fma_f32 v[12:13], v[94:95], v[124:125], v[12:13] op_sel:[0,1,0]
	v_pk_fma_f32 v[130:131], v[32:33], v[26:27], v[130:131] op_sel_hi:[1,0,1]
	v_pk_fma_f32 v[12:13], v[32:33], v[126:127], v[12:13] op_sel_hi:[1,0,1]
	v_pk_fma_f32 v[130:131], v[34:35], v[26:27], v[130:131] op_sel:[0,1,0]
	v_pk_fma_f32 v[12:13], v[34:35], v[126:127], v[12:13] op_sel:[0,1,0]
	v_cvt_pk_f16_f32 v12, v12, v13
	v_add_f32_dpp v130, v130, v130 quad_perm:[1,0,3,2] row_mask:0xf bank_mask:0xf bound_ctrl:1
	v_add_f32_dpp v131, v131, v131 quad_perm:[1,0,3,2] row_mask:0xf bank_mask:0xf bound_ctrl:1
	ds_write2st64_b32 v47, v14, v12 offset0:0 offset1:4
	ds_read_b128 v[12:15], v113 offset:12800
	ds_read_b128 v[116:119], v113 offset:16896
	ds_read_b128 v[120:123], v113 offset:8704
	ds_read_b128 v[124:127], v113 offset:512
	ds_read_b64 v[90:91], v112 offset:256
	v_pk_fma_f32 v[92:93], v[28:29], v[96:97], v[92:93] op_sel_hi:[0,1,1]
	v_add_f32_dpp v130, v130, v130 quad_perm:[2,3,0,1] row_mask:0xf bank_mask:0xf bound_ctrl:1
	v_add_f32_dpp v131, v131, v131 quad_perm:[2,3,0,1] row_mask:0xf bank_mask:0xf bound_ctrl:1
	v_pk_fma_f32 v[94:95], v[28:29], v[96:97], v[94:95] op_sel:[1,0,0]
	v_add_f32_dpp v130, v130, v130 row_half_mirror row_mask:0xf bank_mask:0xf bound_ctrl:1
	v_add_f32_dpp v131, v131, v131 row_half_mirror row_mask:0xf bank_mask:0xf bound_ctrl:1
	v_pk_fma_f32 v[32:33], v[30:31], v[96:97], v[32:33] op_sel_hi:[0,1,1]
	v_pk_fma_f32 v[34:35], v[30:31], v[96:97], v[34:35] op_sel:[1,0,0]
	ds_read_b64 v[96:97], v115 offset:20992
	v_add_f32_dpp v130, v130, v130 row_mirror row_mask:0xf bank_mask:0xf bound_ctrl:1
	v_add_f32_dpp v131, v131, v131 row_mirror row_mask:0xf bank_mask:0xf bound_ctrl:1
	v_pk_fma_f32 v[92:93], v[20:21], v[130:131], v[92:93] op_sel_hi:[0,1,1]
	v_pk_fma_f32 v[94:95], v[20:21], v[130:131], v[94:95] op_sel:[1,0,0]
	v_pk_fma_f32 v[32:33], v[22:23], v[130:131], v[32:33] op_sel_hi:[0,1,1]
	v_pk_fma_f32 v[34:35], v[22:23], v[130:131], v[34:35] op_sel:[1,0,0]
	s_waitcnt lgkmcnt(1)
	v_pk_mul_f32 v[130:131], v[92:93], v[12:13] op_sel_hi:[1,0]
	v_pk_mul_f32 v[20:21], v[92:93], v[16:17] op_sel_hi:[1,0]
	v_pk_fma_f32 v[130:131], v[94:95], v[12:13], v[130:131] op_sel:[0,1,0]
	v_pk_fma_f32 v[20:21], v[94:95], v[16:17], v[20:21] op_sel:[0,1,0]
	v_pk_fma_f32 v[130:131], v[32:33], v[14:15], v[130:131] op_sel_hi:[1,0,1]
	v_pk_fma_f32 v[20:21], v[32:33], v[18:19], v[20:21] op_sel_hi:[1,0,1]
	v_pk_fma_f32 v[130:131], v[34:35], v[14:15], v[130:131] op_sel:[0,1,0]
	v_pk_fma_f32 v[20:21], v[34:35], v[18:19], v[20:21] op_sel:[0,1,0]
	v_cvt_pk_f16_f32 v14, v20, v21
	v_add_f32_dpp v130, v130, v130 quad_perm:[1,0,3,2] row_mask:0xf bank_mask:0xf bound_ctrl:1
	v_add_f32_dpp v131, v131, v131 quad_perm:[1,0,3,2] row_mask:0xf bank_mask:0xf bound_ctrl:1
	ds_read_b128 v[24:27], v114 offset:13312
	ds_read_b128 v[20:23], v114 offset:17408
	ds_read_b128 v[28:31], v114 offset:9216
	ds_read_b128 v[16:19], v114 offset:1024
	v_pk_fma_f32 v[92:93], v[120:121], v[90:91], v[92:93] op_sel_hi:[0,1,1]
	v_add_f32_dpp v130, v130, v130 quad_perm:[2,3,0,1] row_mask:0xf bank_mask:0xf bound_ctrl:1
	v_add_f32_dpp v131, v131, v131 quad_perm:[2,3,0,1] row_mask:0xf bank_mask:0xf bound_ctrl:1
	v_pk_fma_f32 v[94:95], v[120:121], v[90:91], v[94:95] op_sel:[1,0,0]
	v_add_f32_dpp v130, v130, v130 row_half_mirror row_mask:0xf bank_mask:0xf bound_ctrl:1
	v_add_f32_dpp v131, v131, v131 row_half_mirror row_mask:0xf bank_mask:0xf bound_ctrl:1
	v_pk_fma_f32 v[32:33], v[122:123], v[90:91], v[32:33] op_sel_hi:[0,1,1]
	v_pk_fma_f32 v[34:35], v[122:123], v[90:91], v[34:35] op_sel:[1,0,0]
	v_add_f32_dpp v130, v130, v130 row_mirror row_mask:0xf bank_mask:0xf bound_ctrl:1
	v_add_f32_dpp v131, v131, v131 row_mirror row_mask:0xf bank_mask:0xf bound_ctrl:1
	v_pk_fma_f32 v[92:93], v[116:117], v[130:131], v[92:93] op_sel_hi:[0,1,1]
	v_pk_fma_f32 v[94:95], v[116:117], v[130:131], v[94:95] op_sel:[1,0,0]
	v_pk_fma_f32 v[32:33], v[118:119], v[130:131], v[32:33] op_sel_hi:[0,1,1]
	v_pk_fma_f32 v[34:35], v[118:119], v[130:131], v[34:35] op_sel:[1,0,0]
	s_waitcnt lgkmcnt(0)
	v_pk_mul_f32 v[130:131], v[92:93], v[24:25] op_sel_hi:[1,0]
	v_pk_mul_f32 v[12:13], v[92:93], v[124:125] op_sel_hi:[1,0]
	v_pk_fma_f32 v[130:131], v[94:95], v[24:25], v[130:131] op_sel:[0,1,0]
	v_pk_fma_f32 v[12:13], v[94:95], v[124:125], v[12:13] op_sel:[0,1,0]
	v_pk_fma_f32 v[130:131], v[32:33], v[26:27], v[130:131] op_sel_hi:[1,0,1]
	v_pk_fma_f32 v[12:13], v[32:33], v[126:127], v[12:13] op_sel_hi:[1,0,1]
	v_pk_fma_f32 v[130:131], v[34:35], v[26:27], v[130:131] op_sel:[0,1,0]
	v_pk_fma_f32 v[12:13], v[34:35], v[126:127], v[12:13] op_sel:[0,1,0]
	v_cvt_pk_f16_f32 v12, v12, v13
	v_add_f32_dpp v130, v130, v130 quad_perm:[1,0,3,2] row_mask:0xf bank_mask:0xf bound_ctrl:1
	v_add_f32_dpp v131, v131, v131 quad_perm:[1,0,3,2] row_mask:0xf bank_mask:0xf bound_ctrl:1
	ds_write2st64_b32 v47, v14, v12 offset0:8 offset1:12
	ds_read_b128 v[12:15], v113 offset:13312
	ds_read_b128 v[116:119], v113 offset:17408
	ds_read_b128 v[120:123], v113 offset:9216
	ds_read_b128 v[124:127], v113 offset:1024
	ds_read_b64 v[90:91], v112 offset:512
	v_pk_fma_f32 v[92:93], v[28:29], v[96:97], v[92:93] op_sel_hi:[0,1,1]
	v_add_f32_dpp v130, v130, v130 quad_perm:[2,3,0,1] row_mask:0xf bank_mask:0xf bound_ctrl:1
	v_add_f32_dpp v131, v131, v131 quad_perm:[2,3,0,1] row_mask:0xf bank_mask:0xf bound_ctrl:1
	v_pk_fma_f32 v[94:95], v[28:29], v[96:97], v[94:95] op_sel:[1,0,0]
	v_add_f32_dpp v130, v130, v130 row_half_mirror row_mask:0xf bank_mask:0xf bound_ctrl:1
	v_add_f32_dpp v131, v131, v131 row_half_mirror row_mask:0xf bank_mask:0xf bound_ctrl:1
	v_pk_fma_f32 v[32:33], v[30:31], v[96:97], v[32:33] op_sel_hi:[0,1,1]
	v_pk_fma_f32 v[34:35], v[30:31], v[96:97], v[34:35] op_sel:[1,0,0]
	ds_read_b64 v[96:97], v115 offset:21248
	v_add_f32_dpp v130, v130, v130 row_mirror row_mask:0xf bank_mask:0xf bound_ctrl:1
	v_add_f32_dpp v131, v131, v131 row_mirror row_mask:0xf bank_mask:0xf bound_ctrl:1
	v_pk_fma_f32 v[92:93], v[20:21], v[130:131], v[92:93] op_sel_hi:[0,1,1]
	v_pk_fma_f32 v[94:95], v[20:21], v[130:131], v[94:95] op_sel:[1,0,0]
	v_pk_fma_f32 v[32:33], v[22:23], v[130:131], v[32:33] op_sel_hi:[0,1,1]
	v_pk_fma_f32 v[34:35], v[22:23], v[130:131], v[34:35] op_sel:[1,0,0]
	s_waitcnt lgkmcnt(1)
	v_pk_mul_f32 v[130:131], v[92:93], v[12:13] op_sel_hi:[1,0]
	v_pk_mul_f32 v[20:21], v[92:93], v[16:17] op_sel_hi:[1,0]
	v_pk_fma_f32 v[130:131], v[94:95], v[12:13], v[130:131] op_sel:[0,1,0]
	v_pk_fma_f32 v[20:21], v[94:95], v[16:17], v[20:21] op_sel:[0,1,0]
	v_pk_fma_f32 v[130:131], v[32:33], v[14:15], v[130:131] op_sel_hi:[1,0,1]
	v_pk_fma_f32 v[20:21], v[32:33], v[18:19], v[20:21] op_sel_hi:[1,0,1]
	v_pk_fma_f32 v[130:131], v[34:35], v[14:15], v[130:131] op_sel:[0,1,0]
	v_pk_fma_f32 v[20:21], v[34:35], v[18:19], v[20:21] op_sel:[0,1,0]
	v_cvt_pk_f16_f32 v14, v20, v21
	v_add_f32_dpp v130, v130, v130 quad_perm:[1,0,3,2] row_mask:0xf bank_mask:0xf bound_ctrl:1
	v_add_f32_dpp v131, v131, v131 quad_perm:[1,0,3,2] row_mask:0xf bank_mask:0xf bound_ctrl:1
	ds_read_b128 v[24:27], v114 offset:13824
	ds_read_b128 v[20:23], v114 offset:17920
	ds_read_b128 v[28:31], v114 offset:9728
	ds_read_b128 v[16:19], v114 offset:1536
	v_pk_fma_f32 v[92:93], v[120:121], v[90:91], v[92:93] op_sel_hi:[0,1,1]
	v_add_f32_dpp v130, v130, v130 quad_perm:[2,3,0,1] row_mask:0xf bank_mask:0xf bound_ctrl:1
	v_add_f32_dpp v131, v131, v131 quad_perm:[2,3,0,1] row_mask:0xf bank_mask:0xf bound_ctrl:1
	v_pk_fma_f32 v[94:95], v[120:121], v[90:91], v[94:95] op_sel:[1,0,0]
	v_add_f32_dpp v130, v130, v130 row_half_mirror row_mask:0xf bank_mask:0xf bound_ctrl:1
	v_add_f32_dpp v131, v131, v131 row_half_mirror row_mask:0xf bank_mask:0xf bound_ctrl:1
	v_pk_fma_f32 v[32:33], v[122:123], v[90:91], v[32:33] op_sel_hi:[0,1,1]
	v_pk_fma_f32 v[34:35], v[122:123], v[90:91], v[34:35] op_sel:[1,0,0]
	v_add_f32_dpp v130, v130, v130 row_mirror row_mask:0xf bank_mask:0xf bound_ctrl:1
	v_add_f32_dpp v131, v131, v131 row_mirror row_mask:0xf bank_mask:0xf bound_ctrl:1
	v_pk_fma_f32 v[92:93], v[116:117], v[130:131], v[92:93] op_sel_hi:[0,1,1]
	v_pk_fma_f32 v[94:95], v[116:117], v[130:131], v[94:95] op_sel:[1,0,0]
	v_pk_fma_f32 v[32:33], v[118:119], v[130:131], v[32:33] op_sel_hi:[0,1,1]
	v_pk_fma_f32 v[34:35], v[118:119], v[130:131], v[34:35] op_sel:[1,0,0]
	s_waitcnt lgkmcnt(0)
	v_pk_mul_f32 v[130:131], v[92:93], v[24:25] op_sel_hi:[1,0]
	v_pk_mul_f32 v[12:13], v[92:93], v[124:125] op_sel_hi:[1,0]
	v_pk_fma_f32 v[130:131], v[94:95], v[24:25], v[130:131] op_sel:[0,1,0]
	v_pk_fma_f32 v[12:13], v[94:95], v[124:125], v[12:13] op_sel:[0,1,0]
	v_pk_fma_f32 v[130:131], v[32:33], v[26:27], v[130:131] op_sel_hi:[1,0,1]
	v_pk_fma_f32 v[12:13], v[32:33], v[126:127], v[12:13] op_sel_hi:[1,0,1]
	v_pk_fma_f32 v[130:131], v[34:35], v[26:27], v[130:131] op_sel:[0,1,0]
	v_pk_fma_f32 v[12:13], v[34:35], v[126:127], v[12:13] op_sel:[0,1,0]
	v_cvt_pk_f16_f32 v12, v12, v13
	v_add_f32_dpp v130, v130, v130 quad_perm:[1,0,3,2] row_mask:0xf bank_mask:0xf bound_ctrl:1
	v_add_f32_dpp v131, v131, v131 quad_perm:[1,0,3,2] row_mask:0xf bank_mask:0xf bound_ctrl:1
	ds_write2st64_b32 v47, v14, v12 offset0:16 offset1:20
	ds_read_b128 v[12:15], v113 offset:13824
	ds_read_b128 v[116:119], v113 offset:17920
	ds_read_b128 v[120:123], v113 offset:9728
	ds_read_b128 v[124:127], v113 offset:1536
	ds_read_b64 v[90:91], v112 offset:768
	v_pk_fma_f32 v[92:93], v[28:29], v[96:97], v[92:93] op_sel_hi:[0,1,1]
	v_add_f32_dpp v130, v130, v130 quad_perm:[2,3,0,1] row_mask:0xf bank_mask:0xf bound_ctrl:1
	v_add_f32_dpp v131, v131, v131 quad_perm:[2,3,0,1] row_mask:0xf bank_mask:0xf bound_ctrl:1
	v_pk_fma_f32 v[94:95], v[28:29], v[96:97], v[94:95] op_sel:[1,0,0]
	v_add_f32_dpp v130, v130, v130 row_half_mirror row_mask:0xf bank_mask:0xf bound_ctrl:1
	v_add_f32_dpp v131, v131, v131 row_half_mirror row_mask:0xf bank_mask:0xf bound_ctrl:1
	v_pk_fma_f32 v[32:33], v[30:31], v[96:97], v[32:33] op_sel_hi:[0,1,1]
	v_pk_fma_f32 v[34:35], v[30:31], v[96:97], v[34:35] op_sel:[1,0,0]
	ds_read_b64 v[96:97], v115 offset:21504
	v_add_f32_dpp v130, v130, v130 row_mirror row_mask:0xf bank_mask:0xf bound_ctrl:1
	v_add_f32_dpp v131, v131, v131 row_mirror row_mask:0xf bank_mask:0xf bound_ctrl:1
	v_pk_fma_f32 v[92:93], v[20:21], v[130:131], v[92:93] op_sel_hi:[0,1,1]
	v_pk_fma_f32 v[94:95], v[20:21], v[130:131], v[94:95] op_sel:[1,0,0]
	v_pk_fma_f32 v[32:33], v[22:23], v[130:131], v[32:33] op_sel_hi:[0,1,1]
	v_pk_fma_f32 v[34:35], v[22:23], v[130:131], v[34:35] op_sel:[1,0,0]
	s_waitcnt lgkmcnt(1)
	v_pk_mul_f32 v[130:131], v[92:93], v[12:13] op_sel_hi:[1,0]
	v_pk_mul_f32 v[20:21], v[92:93], v[16:17] op_sel_hi:[1,0]
	v_pk_fma_f32 v[130:131], v[94:95], v[12:13], v[130:131] op_sel:[0,1,0]
	v_pk_fma_f32 v[20:21], v[94:95], v[16:17], v[20:21] op_sel:[0,1,0]
	v_pk_fma_f32 v[130:131], v[32:33], v[14:15], v[130:131] op_sel_hi:[1,0,1]
	v_pk_fma_f32 v[20:21], v[32:33], v[18:19], v[20:21] op_sel_hi:[1,0,1]
	v_pk_fma_f32 v[130:131], v[34:35], v[14:15], v[130:131] op_sel:[0,1,0]
	v_pk_fma_f32 v[20:21], v[34:35], v[18:19], v[20:21] op_sel:[0,1,0]
	v_cvt_pk_f16_f32 v14, v20, v21
	v_add_f32_dpp v130, v130, v130 quad_perm:[1,0,3,2] row_mask:0xf bank_mask:0xf bound_ctrl:1
	v_add_f32_dpp v131, v131, v131 quad_perm:[1,0,3,2] row_mask:0xf bank_mask:0xf bound_ctrl:1
	ds_read_b128 v[24:27], v114 offset:14336
	ds_read_b128 v[20:23], v114 offset:18432
	ds_read_b128 v[28:31], v114 offset:10240
	ds_read_b128 v[16:19], v114 offset:2048
	v_pk_fma_f32 v[92:93], v[120:121], v[90:91], v[92:93] op_sel_hi:[0,1,1]
	v_add_f32_dpp v130, v130, v130 quad_perm:[2,3,0,1] row_mask:0xf bank_mask:0xf bound_ctrl:1
	v_add_f32_dpp v131, v131, v131 quad_perm:[2,3,0,1] row_mask:0xf bank_mask:0xf bound_ctrl:1
	v_pk_fma_f32 v[94:95], v[120:121], v[90:91], v[94:95] op_sel:[1,0,0]
	v_add_f32_dpp v130, v130, v130 row_half_mirror row_mask:0xf bank_mask:0xf bound_ctrl:1
	v_add_f32_dpp v131, v131, v131 row_half_mirror row_mask:0xf bank_mask:0xf bound_ctrl:1
	v_pk_fma_f32 v[32:33], v[122:123], v[90:91], v[32:33] op_sel_hi:[0,1,1]
	v_pk_fma_f32 v[34:35], v[122:123], v[90:91], v[34:35] op_sel:[1,0,0]
	v_add_f32_dpp v130, v130, v130 row_mirror row_mask:0xf bank_mask:0xf bound_ctrl:1
	v_add_f32_dpp v131, v131, v131 row_mirror row_mask:0xf bank_mask:0xf bound_ctrl:1
	v_pk_fma_f32 v[92:93], v[116:117], v[130:131], v[92:93] op_sel_hi:[0,1,1]
	v_pk_fma_f32 v[94:95], v[116:117], v[130:131], v[94:95] op_sel:[1,0,0]
	v_pk_fma_f32 v[32:33], v[118:119], v[130:131], v[32:33] op_sel_hi:[0,1,1]
	v_pk_fma_f32 v[34:35], v[118:119], v[130:131], v[34:35] op_sel:[1,0,0]
	s_waitcnt lgkmcnt(0)
	v_pk_mul_f32 v[130:131], v[92:93], v[24:25] op_sel_hi:[1,0]
	v_pk_mul_f32 v[12:13], v[92:93], v[124:125] op_sel_hi:[1,0]
	v_pk_fma_f32 v[130:131], v[94:95], v[24:25], v[130:131] op_sel:[0,1,0]
	v_pk_fma_f32 v[12:13], v[94:95], v[124:125], v[12:13] op_sel:[0,1,0]
	v_pk_fma_f32 v[130:131], v[32:33], v[26:27], v[130:131] op_sel_hi:[1,0,1]
	v_pk_fma_f32 v[12:13], v[32:33], v[126:127], v[12:13] op_sel_hi:[1,0,1]
	v_pk_fma_f32 v[130:131], v[34:35], v[26:27], v[130:131] op_sel:[0,1,0]
	v_pk_fma_f32 v[12:13], v[34:35], v[126:127], v[12:13] op_sel:[0,1,0]
	v_cvt_pk_f16_f32 v12, v12, v13
	v_add_f32_dpp v130, v130, v130 quad_perm:[1,0,3,2] row_mask:0xf bank_mask:0xf bound_ctrl:1
	v_add_f32_dpp v131, v131, v131 quad_perm:[1,0,3,2] row_mask:0xf bank_mask:0xf bound_ctrl:1
	ds_write2st64_b32 v47, v14, v12 offset0:24 offset1:28
	ds_read_b128 v[12:15], v113 offset:14336
	ds_read_b128 v[116:119], v113 offset:18432
	ds_read_b128 v[120:123], v113 offset:10240
	ds_read_b128 v[124:127], v113 offset:2048
	ds_read_b64 v[90:91], v112 offset:1024
	v_pk_fma_f32 v[92:93], v[28:29], v[96:97], v[92:93] op_sel_hi:[0,1,1]
	v_add_f32_dpp v130, v130, v130 quad_perm:[2,3,0,1] row_mask:0xf bank_mask:0xf bound_ctrl:1
	v_add_f32_dpp v131, v131, v131 quad_perm:[2,3,0,1] row_mask:0xf bank_mask:0xf bound_ctrl:1
	v_pk_fma_f32 v[94:95], v[28:29], v[96:97], v[94:95] op_sel:[1,0,0]
	v_add_f32_dpp v130, v130, v130 row_half_mirror row_mask:0xf bank_mask:0xf bound_ctrl:1
	v_add_f32_dpp v131, v131, v131 row_half_mirror row_mask:0xf bank_mask:0xf bound_ctrl:1
	v_pk_fma_f32 v[32:33], v[30:31], v[96:97], v[32:33] op_sel_hi:[0,1,1]
	v_pk_fma_f32 v[34:35], v[30:31], v[96:97], v[34:35] op_sel:[1,0,0]
	ds_read_b64 v[96:97], v115 offset:21760
	v_add_f32_dpp v130, v130, v130 row_mirror row_mask:0xf bank_mask:0xf bound_ctrl:1
	v_add_f32_dpp v131, v131, v131 row_mirror row_mask:0xf bank_mask:0xf bound_ctrl:1
	v_pk_fma_f32 v[92:93], v[20:21], v[130:131], v[92:93] op_sel_hi:[0,1,1]
	v_pk_fma_f32 v[94:95], v[20:21], v[130:131], v[94:95] op_sel:[1,0,0]
	v_pk_fma_f32 v[32:33], v[22:23], v[130:131], v[32:33] op_sel_hi:[0,1,1]
	v_pk_fma_f32 v[34:35], v[22:23], v[130:131], v[34:35] op_sel:[1,0,0]
	s_waitcnt lgkmcnt(1)
	v_pk_mul_f32 v[130:131], v[92:93], v[12:13] op_sel_hi:[1,0]
	v_pk_mul_f32 v[20:21], v[92:93], v[16:17] op_sel_hi:[1,0]
	v_pk_fma_f32 v[130:131], v[94:95], v[12:13], v[130:131] op_sel:[0,1,0]
	v_pk_fma_f32 v[20:21], v[94:95], v[16:17], v[20:21] op_sel:[0,1,0]
	v_pk_fma_f32 v[130:131], v[32:33], v[14:15], v[130:131] op_sel_hi:[1,0,1]
	v_pk_fma_f32 v[20:21], v[32:33], v[18:19], v[20:21] op_sel_hi:[1,0,1]
	v_pk_fma_f32 v[130:131], v[34:35], v[14:15], v[130:131] op_sel:[0,1,0]
	v_pk_fma_f32 v[20:21], v[34:35], v[18:19], v[20:21] op_sel:[0,1,0]
	v_cvt_pk_f16_f32 v14, v20, v21
	v_add_f32_dpp v130, v130, v130 quad_perm:[1,0,3,2] row_mask:0xf bank_mask:0xf bound_ctrl:1
	v_add_f32_dpp v131, v131, v131 quad_perm:[1,0,3,2] row_mask:0xf bank_mask:0xf bound_ctrl:1
	ds_read_b128 v[24:27], v114 offset:14848
	ds_read_b128 v[20:23], v114 offset:18944
	ds_read_b128 v[28:31], v114 offset:10752
	ds_read_b128 v[16:19], v114 offset:2560
	v_pk_fma_f32 v[92:93], v[120:121], v[90:91], v[92:93] op_sel_hi:[0,1,1]
	v_add_f32_dpp v130, v130, v130 quad_perm:[2,3,0,1] row_mask:0xf bank_mask:0xf bound_ctrl:1
	v_add_f32_dpp v131, v131, v131 quad_perm:[2,3,0,1] row_mask:0xf bank_mask:0xf bound_ctrl:1
	v_pk_fma_f32 v[94:95], v[120:121], v[90:91], v[94:95] op_sel:[1,0,0]
	v_add_f32_dpp v130, v130, v130 row_half_mirror row_mask:0xf bank_mask:0xf bound_ctrl:1
	v_add_f32_dpp v131, v131, v131 row_half_mirror row_mask:0xf bank_mask:0xf bound_ctrl:1
	v_pk_fma_f32 v[32:33], v[122:123], v[90:91], v[32:33] op_sel_hi:[0,1,1]
	v_pk_fma_f32 v[34:35], v[122:123], v[90:91], v[34:35] op_sel:[1,0,0]
	v_add_f32_dpp v130, v130, v130 row_mirror row_mask:0xf bank_mask:0xf bound_ctrl:1
	v_add_f32_dpp v131, v131, v131 row_mirror row_mask:0xf bank_mask:0xf bound_ctrl:1
	v_pk_fma_f32 v[92:93], v[116:117], v[130:131], v[92:93] op_sel_hi:[0,1,1]
	v_pk_fma_f32 v[94:95], v[116:117], v[130:131], v[94:95] op_sel:[1,0,0]
	v_pk_fma_f32 v[32:33], v[118:119], v[130:131], v[32:33] op_sel_hi:[0,1,1]
	v_pk_fma_f32 v[34:35], v[118:119], v[130:131], v[34:35] op_sel:[1,0,0]
	s_waitcnt lgkmcnt(0)
	v_pk_mul_f32 v[130:131], v[92:93], v[24:25] op_sel_hi:[1,0]
	v_pk_mul_f32 v[12:13], v[92:93], v[124:125] op_sel_hi:[1,0]
	v_pk_fma_f32 v[130:131], v[94:95], v[24:25], v[130:131] op_sel:[0,1,0]
	v_pk_fma_f32 v[12:13], v[94:95], v[124:125], v[12:13] op_sel:[0,1,0]
	v_pk_fma_f32 v[130:131], v[32:33], v[26:27], v[130:131] op_sel_hi:[1,0,1]
	v_pk_fma_f32 v[12:13], v[32:33], v[126:127], v[12:13] op_sel_hi:[1,0,1]
	v_pk_fma_f32 v[130:131], v[34:35], v[26:27], v[130:131] op_sel:[0,1,0]
	v_pk_fma_f32 v[12:13], v[34:35], v[126:127], v[12:13] op_sel:[0,1,0]
	v_cvt_pk_f16_f32 v12, v12, v13
	v_add_f32_dpp v130, v130, v130 quad_perm:[1,0,3,2] row_mask:0xf bank_mask:0xf bound_ctrl:1
	v_add_f32_dpp v131, v131, v131 quad_perm:[1,0,3,2] row_mask:0xf bank_mask:0xf bound_ctrl:1
	ds_write2st64_b32 v47, v14, v12 offset0:32 offset1:36
	ds_read_b128 v[12:15], v113 offset:14848
	ds_read_b128 v[116:119], v113 offset:18944
	ds_read_b128 v[120:123], v113 offset:10752
	ds_read_b128 v[124:127], v113 offset:2560
	ds_read_b64 v[90:91], v112 offset:1280
	v_pk_fma_f32 v[92:93], v[28:29], v[96:97], v[92:93] op_sel_hi:[0,1,1]
	v_add_f32_dpp v130, v130, v130 quad_perm:[2,3,0,1] row_mask:0xf bank_mask:0xf bound_ctrl:1
	v_add_f32_dpp v131, v131, v131 quad_perm:[2,3,0,1] row_mask:0xf bank_mask:0xf bound_ctrl:1
	v_pk_fma_f32 v[94:95], v[28:29], v[96:97], v[94:95] op_sel:[1,0,0]
	v_add_f32_dpp v130, v130, v130 row_half_mirror row_mask:0xf bank_mask:0xf bound_ctrl:1
	v_add_f32_dpp v131, v131, v131 row_half_mirror row_mask:0xf bank_mask:0xf bound_ctrl:1
	v_pk_fma_f32 v[32:33], v[30:31], v[96:97], v[32:33] op_sel_hi:[0,1,1]
	v_pk_fma_f32 v[34:35], v[30:31], v[96:97], v[34:35] op_sel:[1,0,0]
	ds_read_b64 v[96:97], v115 offset:22016
	v_add_f32_dpp v130, v130, v130 row_mirror row_mask:0xf bank_mask:0xf bound_ctrl:1
	v_add_f32_dpp v131, v131, v131 row_mirror row_mask:0xf bank_mask:0xf bound_ctrl:1
	v_pk_fma_f32 v[92:93], v[20:21], v[130:131], v[92:93] op_sel_hi:[0,1,1]
	v_pk_fma_f32 v[94:95], v[20:21], v[130:131], v[94:95] op_sel:[1,0,0]
	v_pk_fma_f32 v[32:33], v[22:23], v[130:131], v[32:33] op_sel_hi:[0,1,1]
	v_pk_fma_f32 v[34:35], v[22:23], v[130:131], v[34:35] op_sel:[1,0,0]
	s_waitcnt lgkmcnt(1)
	v_pk_mul_f32 v[130:131], v[92:93], v[12:13] op_sel_hi:[1,0]
	v_pk_mul_f32 v[20:21], v[92:93], v[16:17] op_sel_hi:[1,0]
	v_pk_fma_f32 v[130:131], v[94:95], v[12:13], v[130:131] op_sel:[0,1,0]
	v_pk_fma_f32 v[20:21], v[94:95], v[16:17], v[20:21] op_sel:[0,1,0]
	v_pk_fma_f32 v[130:131], v[32:33], v[14:15], v[130:131] op_sel_hi:[1,0,1]
	v_pk_fma_f32 v[20:21], v[32:33], v[18:19], v[20:21] op_sel_hi:[1,0,1]
	v_pk_fma_f32 v[130:131], v[34:35], v[14:15], v[130:131] op_sel:[0,1,0]
	v_pk_fma_f32 v[20:21], v[34:35], v[18:19], v[20:21] op_sel:[0,1,0]
	v_cvt_pk_f16_f32 v14, v20, v21
	v_add_f32_dpp v130, v130, v130 quad_perm:[1,0,3,2] row_mask:0xf bank_mask:0xf bound_ctrl:1
	v_add_f32_dpp v131, v131, v131 quad_perm:[1,0,3,2] row_mask:0xf bank_mask:0xf bound_ctrl:1
	ds_read_b128 v[24:27], v114 offset:15360
	ds_read_b128 v[20:23], v114 offset:19456
	ds_read_b128 v[28:31], v114 offset:11264
	ds_read_b128 v[16:19], v114 offset:3072
	v_pk_fma_f32 v[92:93], v[120:121], v[90:91], v[92:93] op_sel_hi:[0,1,1]
	v_add_f32_dpp v130, v130, v130 quad_perm:[2,3,0,1] row_mask:0xf bank_mask:0xf bound_ctrl:1
	v_add_f32_dpp v131, v131, v131 quad_perm:[2,3,0,1] row_mask:0xf bank_mask:0xf bound_ctrl:1
	v_pk_fma_f32 v[94:95], v[120:121], v[90:91], v[94:95] op_sel:[1,0,0]
	v_add_f32_dpp v130, v130, v130 row_half_mirror row_mask:0xf bank_mask:0xf bound_ctrl:1
	v_add_f32_dpp v131, v131, v131 row_half_mirror row_mask:0xf bank_mask:0xf bound_ctrl:1
	v_pk_fma_f32 v[32:33], v[122:123], v[90:91], v[32:33] op_sel_hi:[0,1,1]
	v_pk_fma_f32 v[34:35], v[122:123], v[90:91], v[34:35] op_sel:[1,0,0]
	v_add_f32_dpp v130, v130, v130 row_mirror row_mask:0xf bank_mask:0xf bound_ctrl:1
	v_add_f32_dpp v131, v131, v131 row_mirror row_mask:0xf bank_mask:0xf bound_ctrl:1
	v_pk_fma_f32 v[92:93], v[116:117], v[130:131], v[92:93] op_sel_hi:[0,1,1]
	v_pk_fma_f32 v[94:95], v[116:117], v[130:131], v[94:95] op_sel:[1,0,0]
	v_pk_fma_f32 v[32:33], v[118:119], v[130:131], v[32:33] op_sel_hi:[0,1,1]
	v_pk_fma_f32 v[34:35], v[118:119], v[130:131], v[34:35] op_sel:[1,0,0]
	s_waitcnt lgkmcnt(0)
	v_pk_mul_f32 v[130:131], v[92:93], v[24:25] op_sel_hi:[1,0]
	v_pk_mul_f32 v[12:13], v[92:93], v[124:125] op_sel_hi:[1,0]
	v_pk_fma_f32 v[130:131], v[94:95], v[24:25], v[130:131] op_sel:[0,1,0]
	v_pk_fma_f32 v[12:13], v[94:95], v[124:125], v[12:13] op_sel:[0,1,0]
	v_pk_fma_f32 v[130:131], v[32:33], v[26:27], v[130:131] op_sel_hi:[1,0,1]
	v_pk_fma_f32 v[12:13], v[32:33], v[126:127], v[12:13] op_sel_hi:[1,0,1]
	v_pk_fma_f32 v[130:131], v[34:35], v[26:27], v[130:131] op_sel:[0,1,0]
	v_pk_fma_f32 v[12:13], v[34:35], v[126:127], v[12:13] op_sel:[0,1,0]
	v_cvt_pk_f16_f32 v12, v12, v13
	v_add_f32_dpp v130, v130, v130 quad_perm:[1,0,3,2] row_mask:0xf bank_mask:0xf bound_ctrl:1
	v_add_f32_dpp v131, v131, v131 quad_perm:[1,0,3,2] row_mask:0xf bank_mask:0xf bound_ctrl:1
	ds_write2st64_b32 v47, v14, v12 offset0:40 offset1:44
	ds_read_b128 v[12:15], v113 offset:15360
	ds_read_b128 v[116:119], v113 offset:19456
	ds_read_b128 v[120:123], v113 offset:11264
	ds_read_b128 v[124:127], v113 offset:3072
	ds_read_b64 v[90:91], v112 offset:1536
	v_pk_fma_f32 v[92:93], v[28:29], v[96:97], v[92:93] op_sel_hi:[0,1,1]
	v_add_f32_dpp v130, v130, v130 quad_perm:[2,3,0,1] row_mask:0xf bank_mask:0xf bound_ctrl:1
	v_add_f32_dpp v131, v131, v131 quad_perm:[2,3,0,1] row_mask:0xf bank_mask:0xf bound_ctrl:1
	v_pk_fma_f32 v[94:95], v[28:29], v[96:97], v[94:95] op_sel:[1,0,0]
	v_add_f32_dpp v130, v130, v130 row_half_mirror row_mask:0xf bank_mask:0xf bound_ctrl:1
	v_add_f32_dpp v131, v131, v131 row_half_mirror row_mask:0xf bank_mask:0xf bound_ctrl:1
	v_pk_fma_f32 v[32:33], v[30:31], v[96:97], v[32:33] op_sel_hi:[0,1,1]
	v_pk_fma_f32 v[34:35], v[30:31], v[96:97], v[34:35] op_sel:[1,0,0]
	ds_read_b64 v[96:97], v115 offset:22272
	v_add_f32_dpp v130, v130, v130 row_mirror row_mask:0xf bank_mask:0xf bound_ctrl:1
	v_add_f32_dpp v131, v131, v131 row_mirror row_mask:0xf bank_mask:0xf bound_ctrl:1
	v_pk_fma_f32 v[92:93], v[20:21], v[130:131], v[92:93] op_sel_hi:[0,1,1]
	v_pk_fma_f32 v[94:95], v[20:21], v[130:131], v[94:95] op_sel:[1,0,0]
	v_pk_fma_f32 v[32:33], v[22:23], v[130:131], v[32:33] op_sel_hi:[0,1,1]
	v_pk_fma_f32 v[34:35], v[22:23], v[130:131], v[34:35] op_sel:[1,0,0]
	s_waitcnt lgkmcnt(1)
	v_pk_mul_f32 v[130:131], v[92:93], v[12:13] op_sel_hi:[1,0]
	v_pk_mul_f32 v[20:21], v[92:93], v[16:17] op_sel_hi:[1,0]
	v_pk_fma_f32 v[130:131], v[94:95], v[12:13], v[130:131] op_sel:[0,1,0]
	v_pk_fma_f32 v[20:21], v[94:95], v[16:17], v[20:21] op_sel:[0,1,0]
	v_pk_fma_f32 v[130:131], v[32:33], v[14:15], v[130:131] op_sel_hi:[1,0,1]
	v_pk_fma_f32 v[20:21], v[32:33], v[18:19], v[20:21] op_sel_hi:[1,0,1]
	v_pk_fma_f32 v[130:131], v[34:35], v[14:15], v[130:131] op_sel:[0,1,0]
	v_pk_fma_f32 v[20:21], v[34:35], v[18:19], v[20:21] op_sel:[0,1,0]
	v_cvt_pk_f16_f32 v14, v20, v21
	v_add_f32_dpp v130, v130, v130 quad_perm:[1,0,3,2] row_mask:0xf bank_mask:0xf bound_ctrl:1
	v_add_f32_dpp v131, v131, v131 quad_perm:[1,0,3,2] row_mask:0xf bank_mask:0xf bound_ctrl:1
	ds_read_b128 v[24:27], v114 offset:15872
	ds_read_b128 v[20:23], v114 offset:19968
	ds_read_b128 v[28:31], v114 offset:11776
	ds_read_b128 v[16:19], v114 offset:3584
	v_pk_fma_f32 v[92:93], v[120:121], v[90:91], v[92:93] op_sel_hi:[0,1,1]
	v_add_f32_dpp v130, v130, v130 quad_perm:[2,3,0,1] row_mask:0xf bank_mask:0xf bound_ctrl:1
	v_add_f32_dpp v131, v131, v131 quad_perm:[2,3,0,1] row_mask:0xf bank_mask:0xf bound_ctrl:1
	v_pk_fma_f32 v[94:95], v[120:121], v[90:91], v[94:95] op_sel:[1,0,0]
	v_add_f32_dpp v130, v130, v130 row_half_mirror row_mask:0xf bank_mask:0xf bound_ctrl:1
	v_add_f32_dpp v131, v131, v131 row_half_mirror row_mask:0xf bank_mask:0xf bound_ctrl:1
	v_pk_fma_f32 v[32:33], v[122:123], v[90:91], v[32:33] op_sel_hi:[0,1,1]
	v_pk_fma_f32 v[34:35], v[122:123], v[90:91], v[34:35] op_sel:[1,0,0]
	v_add_f32_dpp v130, v130, v130 row_mirror row_mask:0xf bank_mask:0xf bound_ctrl:1
	v_add_f32_dpp v131, v131, v131 row_mirror row_mask:0xf bank_mask:0xf bound_ctrl:1
	v_pk_fma_f32 v[92:93], v[116:117], v[130:131], v[92:93] op_sel_hi:[0,1,1]
	v_pk_fma_f32 v[94:95], v[116:117], v[130:131], v[94:95] op_sel:[1,0,0]
	v_pk_fma_f32 v[32:33], v[118:119], v[130:131], v[32:33] op_sel_hi:[0,1,1]
	v_pk_fma_f32 v[34:35], v[118:119], v[130:131], v[34:35] op_sel:[1,0,0]
	s_waitcnt lgkmcnt(0)
	v_pk_mul_f32 v[130:131], v[92:93], v[24:25] op_sel_hi:[1,0]
	v_pk_mul_f32 v[12:13], v[92:93], v[124:125] op_sel_hi:[1,0]
	v_pk_fma_f32 v[130:131], v[94:95], v[24:25], v[130:131] op_sel:[0,1,0]
	v_pk_fma_f32 v[12:13], v[94:95], v[124:125], v[12:13] op_sel:[0,1,0]
	v_pk_fma_f32 v[130:131], v[32:33], v[26:27], v[130:131] op_sel_hi:[1,0,1]
	v_pk_fma_f32 v[12:13], v[32:33], v[126:127], v[12:13] op_sel_hi:[1,0,1]
	v_pk_fma_f32 v[130:131], v[34:35], v[26:27], v[130:131] op_sel:[0,1,0]
	v_pk_fma_f32 v[12:13], v[34:35], v[126:127], v[12:13] op_sel:[0,1,0]
	v_cvt_pk_f16_f32 v12, v12, v13
	v_add_f32_dpp v130, v130, v130 quad_perm:[1,0,3,2] row_mask:0xf bank_mask:0xf bound_ctrl:1
	v_add_f32_dpp v131, v131, v131 quad_perm:[1,0,3,2] row_mask:0xf bank_mask:0xf bound_ctrl:1
	ds_write2st64_b32 v47, v14, v12 offset0:48 offset1:52
	ds_read_b128 v[12:15], v113 offset:15872
	ds_read_b128 v[116:119], v113 offset:19968
	ds_read_b128 v[120:123], v113 offset:11776
	ds_read_b128 v[124:127], v113 offset:3584
	ds_read_b64 v[90:91], v112 offset:1792
	v_pk_fma_f32 v[92:93], v[28:29], v[96:97], v[92:93] op_sel_hi:[0,1,1]
	v_add_f32_dpp v130, v130, v130 quad_perm:[2,3,0,1] row_mask:0xf bank_mask:0xf bound_ctrl:1
	v_add_f32_dpp v131, v131, v131 quad_perm:[2,3,0,1] row_mask:0xf bank_mask:0xf bound_ctrl:1
	v_pk_fma_f32 v[94:95], v[28:29], v[96:97], v[94:95] op_sel:[1,0,0]
	v_add_f32_dpp v130, v130, v130 row_half_mirror row_mask:0xf bank_mask:0xf bound_ctrl:1
	v_add_f32_dpp v131, v131, v131 row_half_mirror row_mask:0xf bank_mask:0xf bound_ctrl:1
	v_pk_fma_f32 v[32:33], v[30:31], v[96:97], v[32:33] op_sel_hi:[0,1,1]
	v_pk_fma_f32 v[34:35], v[30:31], v[96:97], v[34:35] op_sel:[1,0,0]
	ds_read_b64 v[96:97], v115 offset:22272
	v_add_f32_dpp v130, v130, v130 row_mirror row_mask:0xf bank_mask:0xf bound_ctrl:1
	v_add_f32_dpp v131, v131, v131 row_mirror row_mask:0xf bank_mask:0xf bound_ctrl:1
	v_pk_fma_f32 v[92:93], v[20:21], v[130:131], v[92:93] op_sel_hi:[0,1,1]
	v_pk_fma_f32 v[94:95], v[20:21], v[130:131], v[94:95] op_sel:[1,0,0]
	v_pk_fma_f32 v[32:33], v[22:23], v[130:131], v[32:33] op_sel_hi:[0,1,1]
	v_pk_fma_f32 v[34:35], v[22:23], v[130:131], v[34:35] op_sel:[1,0,0]
	s_waitcnt lgkmcnt(1)
	v_pk_mul_f32 v[130:131], v[92:93], v[12:13] op_sel_hi:[1,0]
	v_pk_mul_f32 v[20:21], v[92:93], v[16:17] op_sel_hi:[1,0]
	v_pk_fma_f32 v[130:131], v[94:95], v[12:13], v[130:131] op_sel:[0,1,0]
	v_pk_fma_f32 v[20:21], v[94:95], v[16:17], v[20:21] op_sel:[0,1,0]
	v_pk_fma_f32 v[130:131], v[32:33], v[14:15], v[130:131] op_sel_hi:[1,0,1]
	v_pk_fma_f32 v[20:21], v[32:33], v[18:19], v[20:21] op_sel_hi:[1,0,1]
	v_pk_fma_f32 v[130:131], v[34:35], v[14:15], v[130:131] op_sel:[0,1,0]
	v_pk_fma_f32 v[20:21], v[34:35], v[18:19], v[20:21] op_sel:[0,1,0]
	v_cvt_pk_f16_f32 v14, v20, v21
	v_add_f32_dpp v130, v130, v130 quad_perm:[1,0,3,2] row_mask:0xf bank_mask:0xf bound_ctrl:1
	v_add_f32_dpp v131, v131, v131 quad_perm:[1,0,3,2] row_mask:0xf bank_mask:0xf bound_ctrl:1
	ds_read_b128 v[24:27], v114 offset:15872
	ds_read_b128 v[20:23], v114 offset:19968
	ds_read_b128 v[28:31], v114 offset:11776
	ds_read_b128 v[16:19], v114 offset:3584
	v_pk_fma_f32 v[92:93], v[120:121], v[90:91], v[92:93] op_sel_hi:[0,1,1]
	v_add_f32_dpp v130, v130, v130 quad_perm:[2,3,0,1] row_mask:0xf bank_mask:0xf bound_ctrl:1
	v_add_f32_dpp v131, v131, v131 quad_perm:[2,3,0,1] row_mask:0xf bank_mask:0xf bound_ctrl:1
	v_pk_fma_f32 v[94:95], v[120:121], v[90:91], v[94:95] op_sel:[1,0,0]
	v_add_f32_dpp v130, v130, v130 row_half_mirror row_mask:0xf bank_mask:0xf bound_ctrl:1
	v_add_f32_dpp v131, v131, v131 row_half_mirror row_mask:0xf bank_mask:0xf bound_ctrl:1
	v_pk_fma_f32 v[32:33], v[122:123], v[90:91], v[32:33] op_sel_hi:[0,1,1]
	v_pk_fma_f32 v[34:35], v[122:123], v[90:91], v[34:35] op_sel:[1,0,0]
	v_add_f32_dpp v130, v130, v130 row_mirror row_mask:0xf bank_mask:0xf bound_ctrl:1
	v_add_f32_dpp v131, v131, v131 row_mirror row_mask:0xf bank_mask:0xf bound_ctrl:1
	v_pk_fma_f32 v[92:93], v[116:117], v[130:131], v[92:93] op_sel_hi:[0,1,1]
	v_pk_fma_f32 v[94:95], v[116:117], v[130:131], v[94:95] op_sel:[1,0,0]
	v_pk_fma_f32 v[32:33], v[118:119], v[130:131], v[32:33] op_sel_hi:[0,1,1]
	v_pk_fma_f32 v[34:35], v[118:119], v[130:131], v[34:35] op_sel:[1,0,0]
	v_pk_mul_f32 v[12:13], v[92:93], v[124:125] op_sel_hi:[1,0]
	v_pk_fma_f32 v[12:13], v[94:95], v[124:125], v[12:13] op_sel:[0,1,0]
	v_pk_fma_f32 v[12:13], v[32:33], v[126:127], v[12:13] op_sel_hi:[1,0,1]
	v_pk_fma_f32 v[12:13], v[34:35], v[126:127], v[12:13] op_sel:[0,1,0]
	v_cvt_pk_f16_f32 v12, v12, v13
	ds_write2st64_b32 v47, v14, v12 offset0:56 offset1:60
	ds_read_b128 v[12:15], v114 offset:7936
	s_add_i32 s93, s93, 3
	s_and_b64 vcc, exec, s[82:83]
	s_cbranch_vccz .LBB0_409
	s_waitcnt lgkmcnt(3)
	v_cvt_f32_f16_sdwa v29, v50 dst_sel:DWORD dst_unused:UNUSED_PAD src0_sel:WORD_1
	v_cvt_f32_f16_e32 v28, v50
	v_cvt_f32_f16_sdwa v31, v51 dst_sel:DWORD dst_unused:UNUSED_PAD src0_sel:WORD_1
	v_cvt_f32_f16_e32 v30, v51
	s_waitcnt lgkmcnt(2)
	v_cvt_f32_f16_sdwa v17, v56 dst_sel:DWORD dst_unused:UNUSED_PAD src0_sel:WORD_1
	v_cvt_f32_f16_e32 v16, v56
	v_cvt_f32_f16_sdwa v19, v57 dst_sel:DWORD dst_unused:UNUSED_PAD src0_sel:WORD_1
	v_cvt_f32_f16_e32 v18, v57
	v_pk_mul_f32 v[22:23], v[0:1], v[28:29]
	v_pk_mul_f32 v[20:21], v[2:3], v[30:31]
	s_waitcnt lgkmcnt(2)
	v_pk_mul_f32 v[96:97], v[22:23], v[22:23]
	v_pk_mul_f32 v[90:91], v[20:21], v[20:21]
	v_add_f32_e32 v42, v96, v97
	v_cvt_f32_f16_sdwa v25, v48 dst_sel:DWORD dst_unused:UNUSED_PAD src0_sel:WORD_1
	v_cvt_f32_f16_e32 v24, v48
	v_cvt_f32_f16_sdwa v27, v49 dst_sel:DWORD dst_unused:UNUSED_PAD src0_sel:WORD_1
	v_cvt_f32_f16_e32 v26, v49
	v_add_f32_e32 v42, v90, v42
	v_add_f32_e32 v42, v91, v42
	v_pk_add_f32 v[90:91], v[16:17], -1.0 op_sel_hi:[1,0]
	v_pk_add_f32 v[96:97], v[18:19], -1.0 op_sel_hi:[1,0]
	v_pk_fma_f32 v[90:91], v[4:5], v[90:91], 1.0 op_sel_hi:[1,1,0]
	v_pk_fma_f32 v[96:97], v[6:7], v[96:97], 1.0 op_sel_hi:[1,1,0]
	v_pk_mul_f32 v[90:91], v[28:29], v[90:91]
	v_pk_mul_f32 v[96:97], v[30:31], v[96:97]
	v_pk_mul_f32 v[28:29], v[24:25], v[90:91]
	v_pk_mul_f32 v[30:31], v[26:27], v[96:97]
	v_pk_mul_f32 v[28:29], v[8:9], v[28:29]
	v_pk_mul_f32 v[30:31], v[10:11], v[30:31]
	v_add_f32_e32 v28, v28, v29
	v_add_f32_e32 v29, v30, v31
	v_add_f32_e32 v28, v28, v29
	v_add_f32_dpp v42, v42, v42 quad_perm:[1,0,3,2] row_mask:0xf bank_mask:0xf bound_ctrl:1
	s_nop 0
	v_add_f32_dpp v28, v28, v28 quad_perm:[1,0,3,2] row_mask:0xf bank_mask:0xf bound_ctrl:1
	v_add_f32_dpp v42, v42, v42 quad_perm:[2,3,0,1] row_mask:0xf bank_mask:0xf bound_ctrl:1
	s_nop 0
	v_add_f32_dpp v28, v28, v28 quad_perm:[2,3,0,1] row_mask:0xf bank_mask:0xf bound_ctrl:1
	v_add_f32_dpp v42, v42, v42 row_half_mirror row_mask:0xf bank_mask:0xf bound_ctrl:1
	s_nop 0
	v_add_f32_dpp v28, v28, v28 row_half_mirror row_mask:0xf bank_mask:0xf bound_ctrl:1
	v_mov_b32_dpp v47, v42 row_mirror row_mask:0xf bank_mask:0xf bound_ctrl:1
	s_nop 0
	v_mov_b32_dpp v29, v28 row_mirror row_mask:0xf bank_mask:0xf bound_ctrl:1
	s_and_saveexec_b64 s[12:13], s[6:7]
	s_cbranch_execz .LBB0_442
	s_add_i32 s94, s94, 48
	v_cmp_lt_u32_e32 vcc, s94, v106
	s_and_b64 exec, exec, vcc
	s_cbranch_execz .LBB0_442
	v_add_f32_e32 v30, v28, v29
	v_add_u32_e32 v28, s94, v46
	v_ashrrev_i32_e32 v29, 31, v28
	v_lshlrev_b64 v[28:29], 6, v[28:29]
	v_lshl_add_u64 v[28:29], s[58:59], 0, v[28:29]
	global_store_dword v[28:29], v30, off

.LBB0_444:
	v_swap_b32 v17, v12
	v_swap_b32 v19, v14
	s_and_saveexec_b64 s[6:7], s[4:5]
	s_cbranch_execz .LBB0_402
	ds_read_b128 v[0:3], v105 offset:45056
	ds_read_b128 v[4:7], v105 offset:45072
	s_lshl_b32 s42, s57, 1
	v_lshlrev_b32_e32 v42, 1, v40
	s_waitcnt lgkmcnt(1)
	v_cvt_f32_f16_sdwa v21, v0 dst_sel:DWORD dst_unused:UNUSED_PAD src0_sel:WORD_1
	v_cvt_f32_f16_e32 v20, v0
	v_cvt_f32_f16_sdwa v23, v1 dst_sel:DWORD dst_unused:UNUSED_PAD src0_sel:WORD_1
	v_cvt_f32_f16_e32 v22, v1
	v_cvt_f32_f16_sdwa v25, v2 dst_sel:DWORD dst_unused:UNUSED_PAD src0_sel:WORD_1
	v_cvt_f32_f16_e32 v24, v2
	v_cvt_f32_f16_sdwa v27, v3 dst_sel:DWORD dst_unused:UNUSED_PAD src0_sel:WORD_1
	v_cvt_f32_f16_e32 v26, v3
	ds_read_b128 v[0:3], v105 offset:45088
	ds_read_b128 v[8:11], v105 offset:45104
	v_pk_add_f32 v[20:21], v[20:21], v[22:23]
	s_waitcnt lgkmcnt(2)
	v_cvt_f32_f16_sdwa v29, v7 dst_sel:DWORD dst_unused:UNUSED_PAD src0_sel:WORD_1
	v_pk_add_f32 v[22:23], v[24:25], v[26:27]
	v_cvt_f32_f16_sdwa v25, v4 dst_sel:DWORD dst_unused:UNUSED_PAD src0_sel:WORD_1
	v_cvt_f32_f16_e32 v24, v4
	v_cvt_f32_f16_sdwa v27, v5 dst_sel:DWORD dst_unused:UNUSED_PAD src0_sel:WORD_1
	v_cvt_f32_f16_e32 v26, v5
	v_cvt_f32_f16_sdwa v5, v6 dst_sel:DWORD dst_unused:UNUSED_PAD src0_sel:WORD_1
	v_cvt_f32_f16_e32 v4, v6
	v_cvt_f32_f16_e32 v28, v7
	v_pk_add_f32 v[6:7], v[20:21], v[22:23]
	v_pk_add_f32 v[20:21], v[24:25], v[26:27]
	s_waitcnt lgkmcnt(1)
	v_cvt_f32_f16_sdwa v23, v0 dst_sel:DWORD dst_unused:UNUSED_PAD src0_sel:WORD_1
	v_cvt_f32_f16_e32 v22, v0
	v_cvt_f32_f16_sdwa v25, v1 dst_sel:DWORD dst_unused:UNUSED_PAD src0_sel:WORD_1
	v_cvt_f32_f16_e32 v24, v1
	v_pk_add_f32 v[4:5], v[4:5], v[28:29]
	v_cvt_f32_f16_sdwa v1, v2 dst_sel:DWORD dst_unused:UNUSED_PAD src0_sel:WORD_1
	v_cvt_f32_f16_e32 v0, v2
	v_cvt_f32_f16_sdwa v27, v3 dst_sel:DWORD dst_unused:UNUSED_PAD src0_sel:WORD_1
	v_cvt_f32_f16_e32 v26, v3
	v_pk_add_f32 v[6:7], v[6:7], 0 op_sel_hi:[1,0]
	v_pk_add_f32 v[2:3], v[20:21], v[4:5]
	v_pk_add_f32 v[4:5], v[22:23], v[24:25]
	v_pk_add_f32 v[2:3], v[6:7], v[2:3]
	s_waitcnt lgkmcnt(0)
	v_cvt_f32_f16_sdwa v7, v8 dst_sel:DWORD dst_unused:UNUSED_PAD src0_sel:WORD_1
	v_cvt_f32_f16_e32 v6, v8
	v_cvt_f32_f16_sdwa v21, v9 dst_sel:DWORD dst_unused:UNUSED_PAD src0_sel:WORD_1
	v_cvt_f32_f16_e32 v20, v9
	v_cvt_f32_f16_sdwa v9, v10 dst_sel:DWORD dst_unused:UNUSED_PAD src0_sel:WORD_1
	v_cvt_f32_f16_e32 v8, v10
	v_cvt_f32_f16_sdwa v23, v11 dst_sel:DWORD dst_unused:UNUSED_PAD src0_sel:WORD_1
	v_cvt_f32_f16_e32 v22, v11
	v_pk_add_f32 v[0:1], v[0:1], v[26:27]
	s_nop 0
	v_pk_add_f32 v[0:1], v[4:5], v[0:1]
	v_pk_add_f32 v[4:5], v[8:9], v[22:23]
	v_pk_add_f32 v[0:1], v[2:3], v[0:1]
	v_pk_add_f32 v[2:3], v[6:7], v[20:21]
	s_nop 0
	v_pk_add_f32 v[2:3], v[2:3], v[4:5]
	v_mov_b32_e32 v5, s11
	v_pk_add_f32 v[0:1], v[0:1], v[2:3]
	v_mov_b32_e32 v3, s33
	v_cvt_pk_f16_f32 v4, v0, v1
	v_add_u32_e32 v0, s91, v108
	v_add_u32_e32 v2, 0xffffbf80, v0
	v_cmp_gt_i32_e32 vcc, s87, v0
	v_ashrrev_i32_e32 v1, 31, v0
	s_nop 0
	v_cndmask_b32_e32 v0, v2, v0, vcc
	v_mov_b32_e32 v2, s10
	v_cndmask_b32_e32 v1, 0, v1, vcc
	v_cndmask_b32_e32 v3, v2, v3, vcc
	v_mov_b32_e32 v2, s3
	v_cndmask_b32_e32 v2, v2, v5, vcc
	v_lshlrev_b64 v[0:1], 11, v[0:1]
	v_lshl_add_u64 v[0:1], v[2:3], 0, v[0:1]
	v_lshl_add_u64 v[0:1], v[0:1], 0, s[42:43]
	s_lshl_b32 s42, s92, 1
	v_lshl_add_u64 v[0:1], v[0:1], 0, s[42:43]
	v_lshl_add_u64 v[0:1], v[0:1], 0, v[42:43]
	global_store_dword v[0:1], v4, off
	s_branch .LBB0_402
